# attention row-max DPP steps fused into v_max_f32_dpp; selection prefix counts via v_mbcnt
# speedup vs baseline: 1.2315x; 1.0037x over previous
.LBB0_1884:
	s_sub_i32 s13, 0x100, s40
	s_mov_b32 s40, s12
	s_cmp_lt_i32 s40, 1
	s_cbranch_scc1 .LBB0_2012
	v_cmp_gt_u32_e32 vcc, v64, v65
	s_nop 1
	v_cndmask_b32_e64 v66, 0, 1, vcc
	v_cmp_eq_u32_e32 vcc, v64, v65
	s_nop 1
	v_mbcnt_lo_u32_b32 v68, vcc_lo, 0
	v_mbcnt_hi_u32_b32 v67, vcc_hi, v68
	v_cmp_gt_u32_e64 s[6:7], s13, v67
	s_nop 1
	v_cndmask_b32_e64 v67, 0, 1, s[6:7]
	v_cndmask_b32_e32 v66, v66, v67, vcc
	v_and_b32_e32 v66, 1, v66
	v_cmp_eq_u32_e64 s[8:9], 1, v66
	v_cmp_ne_u32_e64 s[6:7], 0, v66
	s_and_saveexec_b64 s[10:11], s[8:9]
	s_cbranch_execz .LBB0_1887
	v_mbcnt_lo_u32_b32 v67, s6, 0
	v_mbcnt_hi_u32_b32 v66, s7, v67
	v_lshl_add_u32 v66, v66, 2, s43
	ds_write_b32 v66, v186

.LBB0_1888:
	v_cmp_gt_u32_e32 vcc, v63, v65
	s_nop 1
	v_cndmask_b32_e64 v66, 0, 1, vcc
	v_cmp_eq_u32_e32 vcc, v63, v65
	s_nop 1
	v_mbcnt_lo_u32_b32 v68, vcc_lo, 0
	v_mbcnt_hi_u32_b32 v67, vcc_hi, v68
	v_add_u32_e32 v67, s57, v67
	v_cmp_gt_u32_e64 s[6:7], s13, v67
	s_nop 1
	v_cndmask_b32_e64 v67, 0, 1, s[6:7]
	v_cndmask_b32_e32 v66, v66, v67, vcc
	v_and_b32_e32 v66, 1, v66
	v_cmp_eq_u32_e64 s[8:9], 1, v66
	v_cmp_ne_u32_e64 s[6:7], 0, v66
	s_and_saveexec_b64 s[10:11], s[8:9]
	s_cbranch_execz .LBB0_1890
	v_and_b32_e32 v67, s6, v168
	s_lshl_b32 s8, s41, 2
	v_and_b32_e32 v66, s7, v169
	v_bcnt_u32_b32 v67, v67, 0
	s_add_i32 s8, s43, s8
	v_bcnt_u32_b32 v66, v66, v67
	v_lshl_add_u32 v66, v66, 2, s8
	ds_write_b32 v66, v194

.LBB0_1892:
	v_cmp_gt_u32_e32 vcc, v61, v65
	s_nop 1
	v_cndmask_b32_e64 v66, 0, 1, vcc
	v_cmp_eq_u32_e32 vcc, v61, v65
	s_nop 1
	v_mbcnt_lo_u32_b32 v68, vcc_lo, 0
	v_mbcnt_hi_u32_b32 v67, vcc_hi, v68
	v_add_u32_e32 v67, s57, v67
	v_cmp_gt_u32_e64 s[6:7], s13, v67
	s_nop 1
	v_cndmask_b32_e64 v67, 0, 1, s[6:7]
	v_cndmask_b32_e32 v66, v66, v67, vcc
	v_and_b32_e32 v66, 1, v66
	v_cmp_eq_u32_e64 s[8:9], 1, v66
	v_cmp_ne_u32_e64 s[6:7], 0, v66
	s_and_saveexec_b64 s[10:11], s[8:9]
	s_cbranch_execz .LBB0_1894
	v_and_b32_e32 v67, s6, v168
	s_lshl_b32 s8, s41, 2
	v_and_b32_e32 v66, s7, v169
	v_bcnt_u32_b32 v67, v67, 0
	s_add_i32 s8, s43, s8
	v_bcnt_u32_b32 v66, v66, v67
	v_lshl_add_u32 v66, v66, 2, s8
	ds_write_b32 v66, v196

.LBB0_1896:
	v_cmp_gt_u32_e32 vcc, v59, v65
	s_nop 1
	v_cndmask_b32_e64 v66, 0, 1, vcc
	v_cmp_eq_u32_e32 vcc, v59, v65
	s_nop 1
	v_mbcnt_lo_u32_b32 v68, vcc_lo, 0
	v_mbcnt_hi_u32_b32 v67, vcc_hi, v68
	v_add_u32_e32 v67, s57, v67
	v_cmp_gt_u32_e64 s[6:7], s13, v67
	s_nop 1
	v_cndmask_b32_e64 v67, 0, 1, s[6:7]
	v_cndmask_b32_e32 v66, v66, v67, vcc
	v_and_b32_e32 v66, 1, v66
	v_cmp_ne_u32_e64 s[6:7], 0, v66
	v_cmp_eq_u32_e64 s[8:9], 1, v66
	s_nop 0
	v_mbcnt_lo_u32_b32 v67, s6, 0
	v_mbcnt_hi_u32_b32 v66, s7, v67
	v_add_u32_e32 v66, s41, v66
	v_cmp_gt_u32_e64 s[10:11], s48, v66
	s_and_b64 s[10:11], s[8:9], s[10:11]
	s_and_saveexec_b64 s[8:9], s[10:11]
	v_lshl_add_u32 v66, v66, 2, s43
	ds_write_b32 v66, v198
	s_or_b64 exec, exec, s[8:9]
	s_bcnt1_i32_b64 s6, s[6:7]
	s_add_i32 s41, s41, s6
	s_bcnt1_i32_b64 s6, vcc
	s_add_i32 s57, s57, s6
	s_cmpk_lt_i32 s40, 0x181
	s_cbranch_scc0 .LBB0_2022

.LBB0_1900:
	v_cmp_gt_u32_e32 vcc, v57, v65
	s_nop 1
	v_cndmask_b32_e64 v66, 0, 1, vcc
	v_cmp_eq_u32_e32 vcc, v57, v65
	s_nop 1
	v_mbcnt_lo_u32_b32 v68, vcc_lo, 0
	v_mbcnt_hi_u32_b32 v67, vcc_hi, v68
	v_add_u32_e32 v67, s57, v67
	v_cmp_gt_u32_e64 s[6:7], s13, v67
	s_nop 1
	v_cndmask_b32_e64 v67, 0, 1, s[6:7]
	v_cndmask_b32_e32 v66, v66, v67, vcc
	v_and_b32_e32 v66, 1, v66
	v_cmp_ne_u32_e64 s[6:7], 0, v66
	v_cmp_eq_u32_e64 s[8:9], 1, v66
	s_nop 0
	v_mbcnt_lo_u32_b32 v67, s6, 0
	v_mbcnt_hi_u32_b32 v66, s7, v67
	v_add_u32_e32 v66, s41, v66
	v_cmp_gt_u32_e64 s[10:11], s48, v66
	s_and_b64 s[10:11], s[8:9], s[10:11]
	s_and_saveexec_b64 s[8:9], s[10:11]
	v_lshl_add_u32 v66, v66, 2, s43
	ds_write_b32 v66, v200
	s_or_b64 exec, exec, s[8:9]
	s_bcnt1_i32_b64 s6, s[6:7]
	s_add_i32 s41, s41, s6
	s_bcnt1_i32_b64 s6, vcc
	s_add_i32 s57, s57, s6
	s_cmpk_lt_i32 s40, 0x201
	s_cbranch_scc0 .LBB0_2026

.LBB0_1904:
	v_cmp_gt_u32_e32 vcc, v55, v65
	s_nop 1
	v_cndmask_b32_e64 v66, 0, 1, vcc
	v_cmp_eq_u32_e32 vcc, v55, v65
	s_nop 1
	v_mbcnt_lo_u32_b32 v68, vcc_lo, 0
	v_mbcnt_hi_u32_b32 v67, vcc_hi, v68
	v_add_u32_e32 v67, s57, v67
	v_cmp_gt_u32_e64 s[6:7], s13, v67
	s_nop 1
	v_cndmask_b32_e64 v67, 0, 1, s[6:7]
	v_cndmask_b32_e32 v66, v66, v67, vcc
	v_and_b32_e32 v66, 1, v66
	v_cmp_ne_u32_e64 s[6:7], 0, v66
	v_cmp_eq_u32_e64 s[8:9], 1, v66
	s_nop 0
	v_mbcnt_lo_u32_b32 v67, s6, 0
	v_mbcnt_hi_u32_b32 v66, s7, v67
	v_add_u32_e32 v66, s41, v66
	v_cmp_gt_u32_e64 s[10:11], s48, v66
	s_and_b64 s[10:11], s[8:9], s[10:11]
	s_and_saveexec_b64 s[8:9], s[10:11]
	v_lshl_add_u32 v66, v66, 2, s43
	ds_write_b32 v66, v202
	s_or_b64 exec, exec, s[8:9]
	s_bcnt1_i32_b64 s6, s[6:7]
	s_add_i32 s41, s41, s6
	s_bcnt1_i32_b64 s6, vcc
	s_add_i32 s57, s57, s6
	s_cmpk_lt_i32 s40, 0x281
	s_cbranch_scc0 .LBB0_2030

.LBB0_1908:
	v_cmp_gt_u32_e32 vcc, v53, v65
	s_nop 1
	v_cndmask_b32_e64 v66, 0, 1, vcc
	v_cmp_eq_u32_e32 vcc, v53, v65
	s_nop 1
	v_mbcnt_lo_u32_b32 v68, vcc_lo, 0
	v_mbcnt_hi_u32_b32 v67, vcc_hi, v68
	v_add_u32_e32 v67, s57, v67
	v_cmp_gt_u32_e64 s[6:7], s13, v67
	s_nop 1
	v_cndmask_b32_e64 v67, 0, 1, s[6:7]
	v_cndmask_b32_e32 v66, v66, v67, vcc
	v_and_b32_e32 v66, 1, v66
	v_cmp_ne_u32_e64 s[6:7], 0, v66
	v_cmp_eq_u32_e64 s[8:9], 1, v66
	s_nop 0
	v_mbcnt_lo_u32_b32 v67, s6, 0
	v_mbcnt_hi_u32_b32 v66, s7, v67
	v_add_u32_e32 v66, s41, v66
	v_cmp_gt_u32_e64 s[10:11], s48, v66
	s_and_b64 s[10:11], s[8:9], s[10:11]
	s_and_saveexec_b64 s[8:9], s[10:11]
	v_lshl_add_u32 v66, v66, 2, s43
	ds_write_b32 v66, v204
	s_or_b64 exec, exec, s[8:9]
	s_bcnt1_i32_b64 s6, s[6:7]
	s_add_i32 s41, s41, s6
	s_bcnt1_i32_b64 s6, vcc
	s_add_i32 s57, s57, s6
	s_cmpk_lt_i32 s40, 0x301
	s_cbranch_scc0 .LBB0_2034

.LBB0_1912:
	v_cmp_gt_u32_e32 vcc, v51, v65
	s_nop 1
	v_cndmask_b32_e64 v66, 0, 1, vcc
	v_cmp_eq_u32_e32 vcc, v51, v65
	s_nop 1
	v_mbcnt_lo_u32_b32 v68, vcc_lo, 0
	v_mbcnt_hi_u32_b32 v67, vcc_hi, v68
	v_add_u32_e32 v67, s57, v67
	v_cmp_gt_u32_e64 s[6:7], s13, v67
	s_nop 1
	v_cndmask_b32_e64 v67, 0, 1, s[6:7]
	v_cndmask_b32_e32 v66, v66, v67, vcc
	v_and_b32_e32 v66, 1, v66
	v_cmp_ne_u32_e64 s[6:7], 0, v66
	v_cmp_eq_u32_e64 s[8:9], 1, v66
	s_nop 0
	v_mbcnt_lo_u32_b32 v67, s6, 0
	v_mbcnt_hi_u32_b32 v66, s7, v67
	v_add_u32_e32 v66, s41, v66
	v_cmp_gt_u32_e64 s[10:11], s48, v66
	s_and_b64 s[10:11], s[8:9], s[10:11]
	s_and_saveexec_b64 s[8:9], s[10:11]
	v_lshl_add_u32 v66, v66, 2, s43
	ds_write_b32 v66, v206
	s_or_b64 exec, exec, s[8:9]
	s_bcnt1_i32_b64 s6, s[6:7]
	s_add_i32 s41, s41, s6
	s_bcnt1_i32_b64 s6, vcc
	s_add_i32 s57, s57, s6
	s_cmpk_lt_i32 s40, 0x381
	s_cbranch_scc0 .LBB0_2038

.LBB0_1916:
	v_cmp_gt_u32_e32 vcc, v49, v65
	s_nop 1
	v_cndmask_b32_e64 v66, 0, 1, vcc
	v_cmp_eq_u32_e32 vcc, v49, v65
	s_nop 1
	v_mbcnt_lo_u32_b32 v68, vcc_lo, 0
	v_mbcnt_hi_u32_b32 v67, vcc_hi, v68
	v_add_u32_e32 v67, s57, v67
	v_cmp_gt_u32_e64 s[6:7], s13, v67
	s_nop 1
	v_cndmask_b32_e64 v67, 0, 1, s[6:7]
	v_cndmask_b32_e32 v66, v66, v67, vcc
	v_and_b32_e32 v66, 1, v66
	v_cmp_ne_u32_e64 s[6:7], 0, v66
	v_cmp_eq_u32_e64 s[8:9], 1, v66
	s_nop 0
	v_mbcnt_lo_u32_b32 v67, s6, 0
	v_mbcnt_hi_u32_b32 v66, s7, v67
	v_add_u32_e32 v66, s41, v66
	v_cmp_gt_u32_e64 s[10:11], s48, v66
	s_and_b64 s[10:11], s[8:9], s[10:11]
	s_and_saveexec_b64 s[8:9], s[10:11]
	v_lshl_add_u32 v66, v66, 2, s43
	ds_write_b32 v66, v208
	s_or_b64 exec, exec, s[8:9]
	s_bcnt1_i32_b64 s6, s[6:7]
	s_add_i32 s41, s41, s6
	s_bcnt1_i32_b64 s6, vcc
	s_add_i32 s57, s57, s6
	s_cmpk_lt_i32 s40, 0x401
	s_cbranch_scc0 .LBB0_2042

.LBB0_1920:
	v_cmp_gt_u32_e32 vcc, v47, v65
	s_nop 1
	v_cndmask_b32_e64 v66, 0, 1, vcc
	v_cmp_eq_u32_e32 vcc, v47, v65
	s_nop 1
	v_mbcnt_lo_u32_b32 v68, vcc_lo, 0
	v_mbcnt_hi_u32_b32 v67, vcc_hi, v68
	v_add_u32_e32 v67, s57, v67
	v_cmp_gt_u32_e64 s[6:7], s13, v67
	s_nop 1
	v_cndmask_b32_e64 v67, 0, 1, s[6:7]
	v_cndmask_b32_e32 v66, v66, v67, vcc
	v_and_b32_e32 v66, 1, v66
	v_cmp_ne_u32_e64 s[6:7], 0, v66
	v_cmp_eq_u32_e64 s[8:9], 1, v66
	s_nop 0
	v_mbcnt_lo_u32_b32 v67, s6, 0
	v_mbcnt_hi_u32_b32 v66, s7, v67
	v_add_u32_e32 v66, s41, v66
	v_cmp_gt_u32_e64 s[10:11], s48, v66
	s_and_b64 s[10:11], s[8:9], s[10:11]
	s_and_saveexec_b64 s[8:9], s[10:11]
	v_lshl_add_u32 v66, v66, 2, s43
	v_or_b32_e32 v67, 0x440, v186
	ds_write_b32 v66, v67
	s_or_b64 exec, exec, s[8:9]
	s_bcnt1_i32_b64 s6, s[6:7]
	s_add_i32 s41, s41, s6
	s_bcnt1_i32_b64 s6, vcc
	s_add_i32 s57, s57, s6
	s_cmpk_lt_i32 s40, 0x481
	s_cbranch_scc0 .LBB0_2046

.LBB0_1924:
	v_cmp_gt_u32_e32 vcc, v45, v65
	s_nop 1
	v_cndmask_b32_e64 v66, 0, 1, vcc
	v_cmp_eq_u32_e32 vcc, v45, v65
	s_nop 1
	v_mbcnt_lo_u32_b32 v68, vcc_lo, 0
	v_mbcnt_hi_u32_b32 v67, vcc_hi, v68
	v_add_u32_e32 v67, s57, v67
	v_cmp_gt_u32_e64 s[6:7], s13, v67
	s_nop 1
	v_cndmask_b32_e64 v67, 0, 1, s[6:7]
	v_cndmask_b32_e32 v66, v66, v67, vcc
	v_and_b32_e32 v66, 1, v66
	v_cmp_ne_u32_e64 s[6:7], 0, v66
	v_cmp_eq_u32_e64 s[8:9], 1, v66
	s_nop 0
	v_mbcnt_lo_u32_b32 v67, s6, 0
	v_mbcnt_hi_u32_b32 v66, s7, v67
	v_add_u32_e32 v66, s41, v66
	v_cmp_gt_u32_e64 s[10:11], s48, v66
	s_and_b64 s[10:11], s[8:9], s[10:11]
	s_and_saveexec_b64 s[8:9], s[10:11]
	v_lshl_add_u32 v66, v66, 2, s43
	v_or_b32_e32 v67, 0x4c0, v186
	ds_write_b32 v66, v67
	s_or_b64 exec, exec, s[8:9]
	s_bcnt1_i32_b64 s6, s[6:7]
	s_add_i32 s41, s41, s6
	s_bcnt1_i32_b64 s6, vcc
	s_add_i32 s57, s57, s6
	s_cmpk_lt_i32 s40, 0x501
	s_cbranch_scc0 .LBB0_2050

.LBB0_1928:
	v_cmp_gt_u32_e32 vcc, v43, v65
	s_nop 1
	v_cndmask_b32_e64 v66, 0, 1, vcc
	v_cmp_eq_u32_e32 vcc, v43, v65
	s_nop 1
	v_mbcnt_lo_u32_b32 v68, vcc_lo, 0
	v_mbcnt_hi_u32_b32 v67, vcc_hi, v68
	v_add_u32_e32 v67, s57, v67
	v_cmp_gt_u32_e64 s[6:7], s13, v67
	s_nop 1
	v_cndmask_b32_e64 v67, 0, 1, s[6:7]
	v_cndmask_b32_e32 v66, v66, v67, vcc
	v_and_b32_e32 v66, 1, v66
	v_cmp_ne_u32_e64 s[6:7], 0, v66
	v_cmp_eq_u32_e64 s[8:9], 1, v66
	s_nop 0
	v_mbcnt_lo_u32_b32 v67, s6, 0
	v_mbcnt_hi_u32_b32 v66, s7, v67
	v_add_u32_e32 v66, s41, v66
	v_cmp_gt_u32_e64 s[10:11], s48, v66
	s_and_b64 s[10:11], s[8:9], s[10:11]
	s_and_saveexec_b64 s[8:9], s[10:11]
	v_lshl_add_u32 v66, v66, 2, s43
	v_or_b32_e32 v67, 0x540, v186
	ds_write_b32 v66, v67
	s_or_b64 exec, exec, s[8:9]
	s_bcnt1_i32_b64 s6, s[6:7]
	s_add_i32 s41, s41, s6
	s_bcnt1_i32_b64 s6, vcc
	s_add_i32 s57, s57, s6
	s_cmpk_lt_i32 s40, 0x581
	s_cbranch_scc0 .LBB0_2054

.LBB0_1932:
	v_cmp_gt_u32_e32 vcc, v41, v65
	s_nop 1
	v_cndmask_b32_e64 v66, 0, 1, vcc
	v_cmp_eq_u32_e32 vcc, v41, v65
	s_nop 1
	v_mbcnt_lo_u32_b32 v68, vcc_lo, 0
	v_mbcnt_hi_u32_b32 v67, vcc_hi, v68
	v_add_u32_e32 v67, s57, v67
	v_cmp_gt_u32_e64 s[6:7], s13, v67
	s_nop 1
	v_cndmask_b32_e64 v67, 0, 1, s[6:7]
	v_cndmask_b32_e32 v66, v66, v67, vcc
	v_and_b32_e32 v66, 1, v66
	v_cmp_ne_u32_e64 s[6:7], 0, v66
	v_cmp_eq_u32_e64 s[8:9], 1, v66
	s_nop 0
	v_mbcnt_lo_u32_b32 v67, s6, 0
	v_mbcnt_hi_u32_b32 v66, s7, v67
	v_add_u32_e32 v66, s41, v66
	v_cmp_gt_u32_e64 s[10:11], s48, v66
	s_and_b64 s[10:11], s[8:9], s[10:11]
	s_and_saveexec_b64 s[8:9], s[10:11]
	v_lshl_add_u32 v66, v66, 2, s43
	v_or_b32_e32 v67, 0x5c0, v186
	ds_write_b32 v66, v67
	s_or_b64 exec, exec, s[8:9]
	s_bcnt1_i32_b64 s6, s[6:7]
	s_add_i32 s41, s41, s6
	s_bcnt1_i32_b64 s6, vcc
	s_add_i32 s57, s57, s6
	s_cmpk_lt_i32 s40, 0x601
	s_cbranch_scc0 .LBB0_2058

.LBB0_1936:
	v_cmp_gt_u32_e32 vcc, v39, v65
	s_nop 1
	v_cndmask_b32_e64 v66, 0, 1, vcc
	v_cmp_eq_u32_e32 vcc, v39, v65
	s_nop 1
	v_mbcnt_lo_u32_b32 v68, vcc_lo, 0
	v_mbcnt_hi_u32_b32 v67, vcc_hi, v68
	v_add_u32_e32 v67, s57, v67
	v_cmp_gt_u32_e64 s[6:7], s13, v67
	s_nop 1
	v_cndmask_b32_e64 v67, 0, 1, s[6:7]
	v_cndmask_b32_e32 v66, v66, v67, vcc
	v_and_b32_e32 v66, 1, v66
	v_cmp_ne_u32_e64 s[6:7], 0, v66
	v_cmp_eq_u32_e64 s[8:9], 1, v66
	s_nop 0
	v_mbcnt_lo_u32_b32 v67, s6, 0
	v_mbcnt_hi_u32_b32 v66, s7, v67
	v_add_u32_e32 v66, s41, v66
	v_cmp_gt_u32_e64 s[10:11], s48, v66
	s_and_b64 s[10:11], s[8:9], s[10:11]
	s_and_saveexec_b64 s[8:9], s[10:11]
	v_lshl_add_u32 v66, v66, 2, s43
	v_or_b32_e32 v67, 0x640, v186
	ds_write_b32 v66, v67
	s_or_b64 exec, exec, s[8:9]
	s_bcnt1_i32_b64 s6, s[6:7]
	s_add_i32 s41, s41, s6
	s_bcnt1_i32_b64 s6, vcc
	s_add_i32 s57, s57, s6
	s_cmpk_lt_i32 s40, 0x681
	s_cbranch_scc0 .LBB0_2062

.LBB0_1940:
	v_cmp_gt_u32_e32 vcc, v37, v65
	s_nop 1
	v_cndmask_b32_e64 v66, 0, 1, vcc
	v_cmp_eq_u32_e32 vcc, v37, v65
	s_nop 1
	v_mbcnt_lo_u32_b32 v68, vcc_lo, 0
	v_mbcnt_hi_u32_b32 v67, vcc_hi, v68
	v_add_u32_e32 v67, s57, v67
	v_cmp_gt_u32_e64 s[6:7], s13, v67
	s_nop 1
	v_cndmask_b32_e64 v67, 0, 1, s[6:7]
	v_cndmask_b32_e32 v66, v66, v67, vcc
	v_and_b32_e32 v66, 1, v66
	v_cmp_ne_u32_e64 s[6:7], 0, v66
	v_cmp_eq_u32_e64 s[8:9], 1, v66
	s_nop 0
	v_mbcnt_lo_u32_b32 v67, s6, 0
	v_mbcnt_hi_u32_b32 v66, s7, v67
	v_add_u32_e32 v66, s41, v66
	v_cmp_gt_u32_e64 s[10:11], s48, v66
	s_and_b64 s[10:11], s[8:9], s[10:11]
	s_and_saveexec_b64 s[8:9], s[10:11]
	v_lshl_add_u32 v66, v66, 2, s43
	v_or_b32_e32 v67, 0x6c0, v186
	ds_write_b32 v66, v67
	s_or_b64 exec, exec, s[8:9]
	s_bcnt1_i32_b64 s6, s[6:7]
	s_add_i32 s41, s41, s6
	s_bcnt1_i32_b64 s6, vcc
	s_add_i32 s57, s57, s6
	s_cmpk_lt_i32 s40, 0x701
	s_cbranch_scc0 .LBB0_2066

.LBB0_1944:
	v_cmp_gt_u32_e32 vcc, v35, v65
	s_nop 1
	v_cndmask_b32_e64 v66, 0, 1, vcc
	v_cmp_eq_u32_e32 vcc, v35, v65
	s_nop 1
	v_mbcnt_lo_u32_b32 v68, vcc_lo, 0
	v_mbcnt_hi_u32_b32 v67, vcc_hi, v68
	v_add_u32_e32 v67, s57, v67
	v_cmp_gt_u32_e64 s[6:7], s13, v67
	s_nop 1
	v_cndmask_b32_e64 v67, 0, 1, s[6:7]
	v_cndmask_b32_e32 v66, v66, v67, vcc
	v_and_b32_e32 v66, 1, v66
	v_cmp_ne_u32_e64 s[6:7], 0, v66
	v_cmp_eq_u32_e64 s[8:9], 1, v66
	s_nop 0
	v_mbcnt_lo_u32_b32 v67, s6, 0
	v_mbcnt_hi_u32_b32 v66, s7, v67
	v_add_u32_e32 v66, s41, v66
	v_cmp_gt_u32_e64 s[10:11], s48, v66
	s_and_b64 s[10:11], s[8:9], s[10:11]
	s_and_saveexec_b64 s[8:9], s[10:11]
	v_lshl_add_u32 v66, v66, 2, s43
	v_or_b32_e32 v67, 0x740, v186
	ds_write_b32 v66, v67
	s_or_b64 exec, exec, s[8:9]
	s_bcnt1_i32_b64 s6, s[6:7]
	s_add_i32 s41, s41, s6
	s_bcnt1_i32_b64 s6, vcc
	s_add_i32 s57, s57, s6
	s_cmpk_lt_i32 s40, 0x781
	s_cbranch_scc0 .LBB0_2070

.LBB0_1948:
	v_cmp_gt_u32_e32 vcc, v33, v65
	s_nop 1
	v_cndmask_b32_e64 v66, 0, 1, vcc
	v_cmp_eq_u32_e32 vcc, v33, v65
	s_nop 1
	v_mbcnt_lo_u32_b32 v68, vcc_lo, 0
	v_mbcnt_hi_u32_b32 v67, vcc_hi, v68
	v_add_u32_e32 v67, s57, v67
	v_cmp_gt_u32_e64 s[6:7], s13, v67
	s_nop 1
	v_cndmask_b32_e64 v67, 0, 1, s[6:7]
	v_cndmask_b32_e32 v66, v66, v67, vcc
	v_and_b32_e32 v66, 1, v66
	v_cmp_ne_u32_e64 s[6:7], 0, v66
	v_cmp_eq_u32_e64 s[8:9], 1, v66
	s_nop 0
	v_mbcnt_lo_u32_b32 v67, s6, 0
	v_mbcnt_hi_u32_b32 v66, s7, v67
	v_add_u32_e32 v66, s41, v66
	v_cmp_gt_u32_e64 s[10:11], s48, v66
	s_and_b64 s[10:11], s[8:9], s[10:11]
	s_and_saveexec_b64 s[8:9], s[10:11]
	v_lshl_add_u32 v66, v66, 2, s43
	ds_write_b32 v66, v225
	s_or_b64 exec, exec, s[8:9]
	s_bcnt1_i32_b64 s6, s[6:7]
	s_add_i32 s41, s41, s6
	s_bcnt1_i32_b64 s6, vcc
	s_add_i32 s57, s57, s6
	s_cmpk_lt_i32 s40, 0x801
	s_cbranch_scc0 .LBB0_2074

.LBB0_1952:
	v_cmp_gt_u32_e32 vcc, v31, v65
	s_nop 1
	v_cndmask_b32_e64 v66, 0, 1, vcc
	v_cmp_eq_u32_e32 vcc, v31, v65
	s_nop 1
	v_mbcnt_lo_u32_b32 v68, vcc_lo, 0
	v_mbcnt_hi_u32_b32 v67, vcc_hi, v68
	v_add_u32_e32 v67, s57, v67
	v_cmp_gt_u32_e64 s[6:7], s13, v67
	s_nop 1
	v_cndmask_b32_e64 v67, 0, 1, s[6:7]
	v_cndmask_b32_e32 v66, v66, v67, vcc
	v_and_b32_e32 v66, 1, v66
	v_cmp_ne_u32_e64 s[6:7], 0, v66
	v_cmp_eq_u32_e64 s[8:9], 1, v66
	s_nop 0
	v_mbcnt_lo_u32_b32 v67, s6, 0
	v_mbcnt_hi_u32_b32 v66, s7, v67
	v_add_u32_e32 v66, s41, v66
	v_cmp_gt_u32_e64 s[10:11], s48, v66
	s_and_b64 s[10:11], s[8:9], s[10:11]
	s_and_saveexec_b64 s[8:9], s[10:11]
	v_lshl_add_u32 v66, v66, 2, s43
	v_or_b32_e32 v67, 0x840, v186
	ds_write_b32 v66, v67
	s_or_b64 exec, exec, s[8:9]
	s_bcnt1_i32_b64 s6, s[6:7]
	s_add_i32 s41, s41, s6
	s_bcnt1_i32_b64 s6, vcc
	s_add_i32 s57, s57, s6
	s_cmpk_lt_i32 s40, 0x881
	s_cbranch_scc0 .LBB0_2078

.LBB0_1956:
	v_cmp_gt_u32_e32 vcc, v29, v65
	s_nop 1
	v_cndmask_b32_e64 v66, 0, 1, vcc
	v_cmp_eq_u32_e32 vcc, v29, v65
	s_nop 1
	v_mbcnt_lo_u32_b32 v68, vcc_lo, 0
	v_mbcnt_hi_u32_b32 v67, vcc_hi, v68
	v_add_u32_e32 v67, s57, v67
	v_cmp_gt_u32_e64 s[6:7], s13, v67
	s_nop 1
	v_cndmask_b32_e64 v67, 0, 1, s[6:7]
	v_cndmask_b32_e32 v66, v66, v67, vcc
	v_and_b32_e32 v66, 1, v66
	v_cmp_ne_u32_e64 s[6:7], 0, v66
	v_cmp_eq_u32_e64 s[8:9], 1, v66
	s_nop 0
	v_mbcnt_lo_u32_b32 v67, s6, 0
	v_mbcnt_hi_u32_b32 v66, s7, v67
	v_add_u32_e32 v66, s41, v66
	v_cmp_gt_u32_e64 s[10:11], s48, v66
	s_and_b64 s[10:11], s[8:9], s[10:11]
	s_and_saveexec_b64 s[8:9], s[10:11]
	v_lshl_add_u32 v66, v66, 2, s43
	v_or_b32_e32 v67, 0x8c0, v186
	ds_write_b32 v66, v67
	s_or_b64 exec, exec, s[8:9]
	s_bcnt1_i32_b64 s6, s[6:7]
	s_add_i32 s41, s41, s6
	s_bcnt1_i32_b64 s6, vcc
	s_add_i32 s57, s57, s6
	s_cmpk_lt_i32 s40, 0x901
	s_cbranch_scc0 .LBB0_2082

.LBB0_1960:
	v_cmp_gt_u32_e32 vcc, v27, v65
	s_nop 1
	v_cndmask_b32_e64 v66, 0, 1, vcc
	v_cmp_eq_u32_e32 vcc, v27, v65
	s_nop 1
	v_mbcnt_lo_u32_b32 v68, vcc_lo, 0
	v_mbcnt_hi_u32_b32 v67, vcc_hi, v68
	v_add_u32_e32 v67, s57, v67
	v_cmp_gt_u32_e64 s[6:7], s13, v67
	s_nop 1
	v_cndmask_b32_e64 v67, 0, 1, s[6:7]
	v_cndmask_b32_e32 v66, v66, v67, vcc
	v_and_b32_e32 v66, 1, v66
	v_cmp_ne_u32_e64 s[6:7], 0, v66
	v_cmp_eq_u32_e64 s[8:9], 1, v66
	s_nop 0
	v_mbcnt_lo_u32_b32 v67, s6, 0
	v_mbcnt_hi_u32_b32 v66, s7, v67
	v_add_u32_e32 v66, s41, v66
	v_cmp_gt_u32_e64 s[10:11], s48, v66
	s_and_b64 s[10:11], s[8:9], s[10:11]
	s_and_saveexec_b64 s[8:9], s[10:11]
	v_lshl_add_u32 v66, v66, 2, s43
	v_or_b32_e32 v67, 0x940, v186
	ds_write_b32 v66, v67
	s_or_b64 exec, exec, s[8:9]
	s_bcnt1_i32_b64 s6, s[6:7]
	s_add_i32 s41, s41, s6
	s_bcnt1_i32_b64 s6, vcc
	s_add_i32 s57, s57, s6
	s_cmpk_lt_i32 s40, 0x981
	s_cbranch_scc0 .LBB0_2086

.LBB0_1964:
	v_cmp_gt_u32_e32 vcc, v25, v65
	s_nop 1
	v_cndmask_b32_e64 v66, 0, 1, vcc
	v_cmp_eq_u32_e32 vcc, v25, v65
	s_nop 1
	v_mbcnt_lo_u32_b32 v68, vcc_lo, 0
	v_mbcnt_hi_u32_b32 v67, vcc_hi, v68
	v_add_u32_e32 v67, s57, v67
	v_cmp_gt_u32_e64 s[6:7], s13, v67
	s_nop 1
	v_cndmask_b32_e64 v67, 0, 1, s[6:7]
	v_cndmask_b32_e32 v66, v66, v67, vcc
	v_and_b32_e32 v66, 1, v66
	v_cmp_ne_u32_e64 s[6:7], 0, v66
	v_cmp_eq_u32_e64 s[8:9], 1, v66
	s_nop 0
	v_mbcnt_lo_u32_b32 v67, s6, 0
	v_mbcnt_hi_u32_b32 v66, s7, v67
	v_add_u32_e32 v66, s41, v66
	v_cmp_gt_u32_e64 s[10:11], s48, v66
	s_and_b64 s[10:11], s[8:9], s[10:11]
	s_and_saveexec_b64 s[8:9], s[10:11]
	v_lshl_add_u32 v66, v66, 2, s43
	v_or_b32_e32 v67, 0x9c0, v186
	ds_write_b32 v66, v67
	s_or_b64 exec, exec, s[8:9]
	s_bcnt1_i32_b64 s6, s[6:7]
	s_add_i32 s41, s41, s6
	s_bcnt1_i32_b64 s6, vcc
	s_add_i32 s57, s57, s6
	s_cmpk_lt_i32 s40, 0xa01
	s_cbranch_scc0 .LBB0_2090

.LBB0_1968:
	v_cmp_gt_u32_e32 vcc, v23, v65
	s_nop 1
	v_cndmask_b32_e64 v66, 0, 1, vcc
	v_cmp_eq_u32_e32 vcc, v23, v65
	s_nop 1
	v_mbcnt_lo_u32_b32 v68, vcc_lo, 0
	v_mbcnt_hi_u32_b32 v67, vcc_hi, v68
	v_add_u32_e32 v67, s57, v67
	v_cmp_gt_u32_e64 s[6:7], s13, v67
	s_nop 1
	v_cndmask_b32_e64 v67, 0, 1, s[6:7]
	v_cndmask_b32_e32 v66, v66, v67, vcc
	v_and_b32_e32 v66, 1, v66
	v_cmp_ne_u32_e64 s[6:7], 0, v66
	v_cmp_eq_u32_e64 s[8:9], 1, v66
	s_nop 0
	v_mbcnt_lo_u32_b32 v67, s6, 0
	v_mbcnt_hi_u32_b32 v66, s7, v67
	v_add_u32_e32 v66, s41, v66
	v_cmp_gt_u32_e64 s[10:11], s48, v66
	s_and_b64 s[10:11], s[8:9], s[10:11]
	s_and_saveexec_b64 s[8:9], s[10:11]
	v_lshl_add_u32 v66, v66, 2, s43
	v_or_b32_e32 v67, 0xa40, v186
	ds_write_b32 v66, v67
	s_or_b64 exec, exec, s[8:9]
	s_bcnt1_i32_b64 s6, s[6:7]
	s_add_i32 s41, s41, s6
	s_bcnt1_i32_b64 s6, vcc
	s_add_i32 s57, s57, s6
	s_cmpk_lt_i32 s40, 0xa81
	s_cbranch_scc0 .LBB0_2094

.LBB0_1972:
	v_cmp_gt_u32_e32 vcc, v21, v65
	s_nop 1
	v_cndmask_b32_e64 v66, 0, 1, vcc
	v_cmp_eq_u32_e32 vcc, v21, v65
	s_nop 1
	v_mbcnt_lo_u32_b32 v68, vcc_lo, 0
	v_mbcnt_hi_u32_b32 v67, vcc_hi, v68
	v_add_u32_e32 v67, s57, v67
	v_cmp_gt_u32_e64 s[6:7], s13, v67
	s_nop 1
	v_cndmask_b32_e64 v67, 0, 1, s[6:7]
	v_cndmask_b32_e32 v66, v66, v67, vcc
	v_and_b32_e32 v66, 1, v66
	v_cmp_ne_u32_e64 s[6:7], 0, v66
	v_cmp_eq_u32_e64 s[8:9], 1, v66
	s_nop 0
	v_mbcnt_lo_u32_b32 v67, s6, 0
	v_mbcnt_hi_u32_b32 v66, s7, v67
	v_add_u32_e32 v66, s41, v66
	v_cmp_gt_u32_e64 s[10:11], s48, v66
	s_and_b64 s[10:11], s[8:9], s[10:11]
	s_and_saveexec_b64 s[8:9], s[10:11]
	v_lshl_add_u32 v66, v66, 2, s43
	v_or_b32_e32 v67, 0xac0, v186
	ds_write_b32 v66, v67
	s_or_b64 exec, exec, s[8:9]
	s_bcnt1_i32_b64 s6, s[6:7]
	s_add_i32 s41, s41, s6
	s_bcnt1_i32_b64 s6, vcc
	s_add_i32 s57, s57, s6
	s_cmpk_lt_i32 s40, 0xb01
	s_cbranch_scc0 .LBB0_2098

.LBB0_1976:
	v_cmp_gt_u32_e32 vcc, v19, v65
	s_nop 1
	v_cndmask_b32_e64 v66, 0, 1, vcc
	v_cmp_eq_u32_e32 vcc, v19, v65
	s_nop 1
	v_mbcnt_lo_u32_b32 v68, vcc_lo, 0
	v_mbcnt_hi_u32_b32 v67, vcc_hi, v68
	v_add_u32_e32 v67, s57, v67
	v_cmp_gt_u32_e64 s[6:7], s13, v67
	s_nop 1
	v_cndmask_b32_e64 v67, 0, 1, s[6:7]
	v_cndmask_b32_e32 v66, v66, v67, vcc
	v_and_b32_e32 v66, 1, v66
	v_cmp_ne_u32_e64 s[6:7], 0, v66
	v_cmp_eq_u32_e64 s[8:9], 1, v66
	s_nop 0
	v_mbcnt_lo_u32_b32 v67, s6, 0
	v_mbcnt_hi_u32_b32 v66, s7, v67
	v_add_u32_e32 v66, s41, v66
	v_cmp_gt_u32_e64 s[10:11], s48, v66
	s_and_b64 s[10:11], s[8:9], s[10:11]
	s_and_saveexec_b64 s[8:9], s[10:11]
	v_lshl_add_u32 v66, v66, 2, s43
	v_or_b32_e32 v67, 0xb40, v186
	ds_write_b32 v66, v67
	s_or_b64 exec, exec, s[8:9]
	s_bcnt1_i32_b64 s6, s[6:7]
	s_add_i32 s41, s41, s6
	s_bcnt1_i32_b64 s6, vcc
	s_add_i32 s57, s57, s6
	s_cmpk_lt_i32 s40, 0xb81
	s_cbranch_scc0 .LBB0_2102

.LBB0_1980:
	v_cmp_gt_u32_e32 vcc, v17, v65
	s_nop 1
	v_cndmask_b32_e64 v66, 0, 1, vcc
	v_cmp_eq_u32_e32 vcc, v17, v65
	s_nop 1
	v_mbcnt_lo_u32_b32 v68, vcc_lo, 0
	v_mbcnt_hi_u32_b32 v67, vcc_hi, v68
	v_add_u32_e32 v67, s57, v67
	v_cmp_gt_u32_e64 s[6:7], s13, v67
	s_nop 1
	v_cndmask_b32_e64 v67, 0, 1, s[6:7]
	v_cndmask_b32_e32 v66, v66, v67, vcc
	v_and_b32_e32 v66, 1, v66
	v_cmp_ne_u32_e64 s[6:7], 0, v66
	v_cmp_eq_u32_e64 s[8:9], 1, v66
	s_nop 0
	v_mbcnt_lo_u32_b32 v67, s6, 0
	v_mbcnt_hi_u32_b32 v66, s7, v67
	v_add_u32_e32 v66, s41, v66
	v_cmp_gt_u32_e64 s[10:11], s48, v66
	s_and_b64 s[10:11], s[8:9], s[10:11]
	s_and_saveexec_b64 s[8:9], s[10:11]
	v_lshl_add_u32 v66, v66, 2, s43
	ds_write_b32 v66, v241
	s_or_b64 exec, exec, s[8:9]
	s_bcnt1_i32_b64 s6, s[6:7]
	s_add_i32 s41, s41, s6
	s_bcnt1_i32_b64 s6, vcc
	s_add_i32 s57, s57, s6
	s_cmpk_lt_i32 s40, 0xc01
	s_cbranch_scc0 .LBB0_2106

.LBB0_1984:
	v_cmp_gt_u32_e32 vcc, v15, v65
	s_nop 1
	v_cndmask_b32_e64 v66, 0, 1, vcc
	v_cmp_eq_u32_e32 vcc, v15, v65
	s_nop 1
	v_mbcnt_lo_u32_b32 v68, vcc_lo, 0
	v_mbcnt_hi_u32_b32 v67, vcc_hi, v68
	v_add_u32_e32 v67, s57, v67
	v_cmp_gt_u32_e64 s[6:7], s13, v67
	s_nop 1
	v_cndmask_b32_e64 v67, 0, 1, s[6:7]
	v_cndmask_b32_e32 v66, v66, v67, vcc
	v_and_b32_e32 v66, 1, v66
	v_cmp_ne_u32_e64 s[6:7], 0, v66
	v_cmp_eq_u32_e64 s[8:9], 1, v66
	s_nop 0
	v_mbcnt_lo_u32_b32 v67, s6, 0
	v_mbcnt_hi_u32_b32 v66, s7, v67
	v_add_u32_e32 v66, s41, v66
	v_cmp_gt_u32_e64 s[10:11], s48, v66
	s_and_b64 s[10:11], s[8:9], s[10:11]
	s_and_saveexec_b64 s[8:9], s[10:11]
	v_lshl_add_u32 v66, v66, 2, s43
	v_or_b32_e32 v67, 0xc40, v186
	ds_write_b32 v66, v67
	s_or_b64 exec, exec, s[8:9]
	s_bcnt1_i32_b64 s6, s[6:7]
	s_add_i32 s41, s41, s6
	s_bcnt1_i32_b64 s6, vcc
	s_add_i32 s57, s57, s6
	s_cmpk_lt_i32 s40, 0xc81
	s_cbranch_scc0 .LBB0_2110

.LBB0_1988:
	v_cmp_gt_u32_e32 vcc, v13, v65
	s_nop 1
	v_cndmask_b32_e64 v66, 0, 1, vcc
	v_cmp_eq_u32_e32 vcc, v13, v65
	s_nop 1
	v_mbcnt_lo_u32_b32 v68, vcc_lo, 0
	v_mbcnt_hi_u32_b32 v67, vcc_hi, v68
	v_add_u32_e32 v67, s57, v67
	v_cmp_gt_u32_e64 s[6:7], s13, v67
	s_nop 1
	v_cndmask_b32_e64 v67, 0, 1, s[6:7]
	v_cndmask_b32_e32 v66, v66, v67, vcc
	v_and_b32_e32 v66, 1, v66
	v_cmp_ne_u32_e64 s[6:7], 0, v66
	v_cmp_eq_u32_e64 s[8:9], 1, v66
	s_nop 0
	v_mbcnt_lo_u32_b32 v67, s6, 0
	v_mbcnt_hi_u32_b32 v66, s7, v67
	v_add_u32_e32 v66, s41, v66
	v_cmp_gt_u32_e64 s[10:11], s48, v66
	s_and_b64 s[10:11], s[8:9], s[10:11]
	s_and_saveexec_b64 s[8:9], s[10:11]
	v_lshl_add_u32 v66, v66, 2, s43
	v_or_b32_e32 v67, 0xcc0, v186
	ds_write_b32 v66, v67
	s_or_b64 exec, exec, s[8:9]
	s_bcnt1_i32_b64 s6, s[6:7]
	s_add_i32 s41, s41, s6
	s_bcnt1_i32_b64 s6, vcc
	s_add_i32 s57, s57, s6
	s_cmpk_lt_i32 s40, 0xd01
	s_cbranch_scc0 .LBB0_2114

.LBB0_1992:
	v_cmp_gt_u32_e32 vcc, v11, v65
	s_nop 1
	v_cndmask_b32_e64 v66, 0, 1, vcc
	v_cmp_eq_u32_e32 vcc, v11, v65
	s_nop 1
	v_mbcnt_lo_u32_b32 v68, vcc_lo, 0
	v_mbcnt_hi_u32_b32 v67, vcc_hi, v68
	v_add_u32_e32 v67, s57, v67
	v_cmp_gt_u32_e64 s[6:7], s13, v67
	s_nop 1
	v_cndmask_b32_e64 v67, 0, 1, s[6:7]
	v_cndmask_b32_e32 v66, v66, v67, vcc
	v_and_b32_e32 v66, 1, v66
	v_cmp_ne_u32_e64 s[6:7], 0, v66
	v_cmp_eq_u32_e64 s[8:9], 1, v66
	s_nop 0
	v_mbcnt_lo_u32_b32 v67, s6, 0
	v_mbcnt_hi_u32_b32 v66, s7, v67
	v_add_u32_e32 v66, s41, v66
	v_cmp_gt_u32_e64 s[10:11], s48, v66
	s_and_b64 s[10:11], s[8:9], s[10:11]
	s_and_saveexec_b64 s[8:9], s[10:11]
	v_lshl_add_u32 v66, v66, 2, s43
	ds_write_b32 v66, v247
	s_or_b64 exec, exec, s[8:9]
	s_bcnt1_i32_b64 s6, s[6:7]
	s_add_i32 s41, s41, s6
	s_bcnt1_i32_b64 s6, vcc
	s_add_i32 s57, s57, s6
	s_cmpk_lt_i32 s40, 0xd81
	s_cbranch_scc0 .LBB0_2118

.LBB0_1996:
	v_cmp_gt_u32_e32 vcc, v9, v65
	s_nop 1
	v_cndmask_b32_e64 v66, 0, 1, vcc
	v_cmp_eq_u32_e32 vcc, v9, v65
	s_nop 1
	v_mbcnt_lo_u32_b32 v68, vcc_lo, 0
	v_mbcnt_hi_u32_b32 v67, vcc_hi, v68
	v_add_u32_e32 v67, s57, v67
	v_cmp_gt_u32_e64 s[6:7], s13, v67
	s_nop 1
	v_cndmask_b32_e64 v67, 0, 1, s[6:7]
	v_cndmask_b32_e32 v66, v66, v67, vcc
	v_and_b32_e32 v66, 1, v66
	v_cmp_ne_u32_e64 s[6:7], 0, v66
	v_cmp_eq_u32_e64 s[8:9], 1, v66
	s_nop 0
	v_mbcnt_lo_u32_b32 v67, s6, 0
	v_mbcnt_hi_u32_b32 v66, s7, v67
	v_add_u32_e32 v66, s41, v66
	v_cmp_gt_u32_e64 s[10:11], s48, v66
	s_and_b64 s[10:11], s[8:9], s[10:11]
	s_and_saveexec_b64 s[8:9], s[10:11]
	v_lshl_add_u32 v66, v66, 2, s43
	ds_write_b32 v66, v249
	s_or_b64 exec, exec, s[8:9]
	s_bcnt1_i32_b64 s6, s[6:7]
	s_add_i32 s41, s41, s6
	s_bcnt1_i32_b64 s6, vcc
	s_add_i32 s57, s57, s6
	s_cmpk_lt_i32 s40, 0xe01
	s_cbranch_scc0 .LBB0_2122

.LBB0_2000:
	v_cmp_gt_u32_e32 vcc, v7, v65
	s_nop 1
	v_cndmask_b32_e64 v66, 0, 1, vcc
	v_cmp_eq_u32_e32 vcc, v7, v65
	s_nop 1
	v_mbcnt_lo_u32_b32 v68, vcc_lo, 0
	v_mbcnt_hi_u32_b32 v67, vcc_hi, v68
	v_add_u32_e32 v67, s57, v67
	v_cmp_gt_u32_e64 s[6:7], s13, v67
	s_nop 1
	v_cndmask_b32_e64 v67, 0, 1, s[6:7]
	v_cndmask_b32_e32 v66, v66, v67, vcc
	v_and_b32_e32 v66, 1, v66
	v_cmp_ne_u32_e64 s[6:7], 0, v66
	v_cmp_eq_u32_e64 s[8:9], 1, v66
	s_nop 0
	v_mbcnt_lo_u32_b32 v67, s6, 0
	v_mbcnt_hi_u32_b32 v66, s7, v67
	v_add_u32_e32 v66, s41, v66
	v_cmp_gt_u32_e64 s[10:11], s48, v66
	s_and_b64 s[10:11], s[8:9], s[10:11]
	s_and_saveexec_b64 s[8:9], s[10:11]
	v_lshl_add_u32 v66, v66, 2, s43
	ds_write_b32 v66, v251
	s_or_b64 exec, exec, s[8:9]
	s_bcnt1_i32_b64 s6, s[6:7]
	s_add_i32 s41, s41, s6
	s_bcnt1_i32_b64 s6, vcc
	s_add_i32 s57, s57, s6
	s_cmpk_lt_i32 s40, 0xe81
	s_cbranch_scc0 .LBB0_2126

.LBB0_2004:
	v_cmp_gt_u32_e32 vcc, v5, v65
	s_nop 1
	v_cndmask_b32_e64 v66, 0, 1, vcc
	v_cmp_eq_u32_e32 vcc, v5, v65
	s_nop 1
	v_mbcnt_lo_u32_b32 v68, vcc_lo, 0
	v_mbcnt_hi_u32_b32 v67, vcc_hi, v68
	v_add_u32_e32 v67, s57, v67
	v_cmp_gt_u32_e64 s[6:7], s13, v67
	s_nop 1
	v_cndmask_b32_e64 v67, 0, 1, s[6:7]
	v_cndmask_b32_e32 v66, v66, v67, vcc
	v_and_b32_e32 v66, 1, v66
	v_cmp_ne_u32_e64 s[6:7], 0, v66
	v_cmp_eq_u32_e64 s[8:9], 1, v66
	s_nop 0
	v_mbcnt_lo_u32_b32 v67, s6, 0
	v_mbcnt_hi_u32_b32 v66, s7, v67
	v_add_u32_e32 v66, s41, v66
	v_cmp_gt_u32_e64 s[10:11], s48, v66
	s_and_b64 s[10:11], s[8:9], s[10:11]
	s_and_saveexec_b64 s[8:9], s[10:11]
	v_lshl_add_u32 v66, v66, 2, s43
	ds_write_b32 v66, v253
	s_or_b64 exec, exec, s[8:9]
	s_bcnt1_i32_b64 s6, s[6:7]
	s_add_i32 s41, s41, s6
	s_bcnt1_i32_b64 s6, vcc
	s_add_i32 s57, s57, s6
	s_cmpk_lt_i32 s40, 0xf01
	s_cbranch_scc0 .LBB0_2130

.LBB0_2008:
	v_cmp_gt_u32_e32 vcc, v3, v65
	s_nop 1
	v_cndmask_b32_e64 v66, 0, 1, vcc
	v_cmp_eq_u32_e32 vcc, v3, v65
	s_nop 1
	v_mbcnt_lo_u32_b32 v68, vcc_lo, 0
	v_mbcnt_hi_u32_b32 v67, vcc_hi, v68
	v_add_u32_e32 v67, s57, v67
	v_cmp_gt_u32_e64 s[6:7], s13, v67
	s_nop 1
	v_cndmask_b32_e64 v67, 0, 1, s[6:7]
	v_cndmask_b32_e32 v66, v66, v67, vcc
	v_and_b32_e32 v66, 1, v66
	v_cmp_ne_u32_e64 s[6:7], 0, v66
	v_cmp_eq_u32_e64 s[8:9], 1, v66
	s_nop 0
	v_mbcnt_lo_u32_b32 v67, s6, 0
	v_mbcnt_hi_u32_b32 v66, s7, v67
	v_add_u32_e32 v66, s41, v66
	v_cmp_gt_u32_e64 s[10:11], s48, v66
	s_and_b64 s[10:11], s[8:9], s[10:11]
	s_and_saveexec_b64 s[8:9], s[10:11]
	v_lshl_add_u32 v66, v66, 2, s43
	ds_write_b32 v66, v255
	s_or_b64 exec, exec, s[8:9]
	s_bcnt1_i32_b64 s6, s[6:7]
	s_add_i32 s41, s41, s6
	s_bcnt1_i32_b64 s6, vcc
	s_add_i32 s57, s57, s6
	s_cmpk_lt_i32 s40, 0xf81
	s_cbranch_scc0 .LBB0_2134

.LBB0_2014:
	v_cmp_gt_u32_e32 vcc, v62, v65
	s_nop 1
	v_cndmask_b32_e64 v66, 0, 1, vcc
	v_cmp_eq_u32_e32 vcc, v62, v65
	s_nop 1
	v_mbcnt_lo_u32_b32 v68, vcc_lo, 0
	v_mbcnt_hi_u32_b32 v67, vcc_hi, v68
	v_add_u32_e32 v67, s57, v67
	v_cmp_gt_u32_e64 s[6:7], s13, v67
	s_nop 1
	v_cndmask_b32_e64 v67, 0, 1, s[6:7]
	v_cndmask_b32_e32 v66, v66, v67, vcc
	v_and_b32_e32 v66, 1, v66
	v_cmp_eq_u32_e64 s[8:9], 1, v66
	v_cmp_ne_u32_e64 s[6:7], 0, v66
	s_and_saveexec_b64 s[10:11], s[8:9]
	s_cbranch_execz .LBB0_2016
	v_and_b32_e32 v67, s6, v168
	s_lshl_b32 s8, s41, 2
	v_and_b32_e32 v66, s7, v169
	v_bcnt_u32_b32 v67, v67, 0
	s_add_i32 s8, s43, s8
	v_bcnt_u32_b32 v66, v66, v67
	v_lshl_add_u32 v66, v66, 2, s8
	ds_write_b32 v66, v195

.LBB0_2018:
	v_cmp_gt_u32_e32 vcc, v60, v65
	s_nop 1
	v_cndmask_b32_e64 v66, 0, 1, vcc
	v_cmp_eq_u32_e32 vcc, v60, v65
	s_nop 1
	v_mbcnt_lo_u32_b32 v68, vcc_lo, 0
	v_mbcnt_hi_u32_b32 v67, vcc_hi, v68
	v_add_u32_e32 v67, s57, v67
	v_cmp_gt_u32_e64 s[6:7], s13, v67
	s_nop 1
	v_cndmask_b32_e64 v67, 0, 1, s[6:7]
	v_cndmask_b32_e32 v66, v66, v67, vcc
	v_and_b32_e32 v66, 1, v66
	v_cmp_ne_u32_e64 s[6:7], 0, v66
	v_cmp_eq_u32_e64 s[8:9], 1, v66
	s_nop 0
	v_mbcnt_lo_u32_b32 v67, s6, 0
	v_mbcnt_hi_u32_b32 v66, s7, v67
	v_add_u32_e32 v66, s41, v66
	v_cmp_gt_u32_e64 s[10:11], s48, v66
	s_and_b64 s[10:11], s[8:9], s[10:11]
	s_and_saveexec_b64 s[8:9], s[10:11]
	v_lshl_add_u32 v66, v66, 2, s43
	ds_write_b32 v66, v197
	s_or_b64 exec, exec, s[8:9]
	s_bcnt1_i32_b64 s6, s[6:7]
	s_add_i32 s41, s41, s6
	s_bcnt1_i32_b64 s6, vcc
	s_add_i32 s57, s57, s6
	s_cmpk_lt_i32 s40, 0x141
	s_cbranch_scc0 .LBB0_1896

.LBB0_2022:
	v_cmp_gt_u32_e32 vcc, v58, v65
	s_nop 1
	v_cndmask_b32_e64 v66, 0, 1, vcc
	v_cmp_eq_u32_e32 vcc, v58, v65
	s_nop 1
	v_mbcnt_lo_u32_b32 v68, vcc_lo, 0
	v_mbcnt_hi_u32_b32 v67, vcc_hi, v68
	v_add_u32_e32 v67, s57, v67
	v_cmp_gt_u32_e64 s[6:7], s13, v67
	s_nop 1
	v_cndmask_b32_e64 v67, 0, 1, s[6:7]
	v_cndmask_b32_e32 v66, v66, v67, vcc
	v_and_b32_e32 v66, 1, v66
	v_cmp_ne_u32_e64 s[6:7], 0, v66
	v_cmp_eq_u32_e64 s[8:9], 1, v66
	s_nop 0
	v_mbcnt_lo_u32_b32 v67, s6, 0
	v_mbcnt_hi_u32_b32 v66, s7, v67
	v_add_u32_e32 v66, s41, v66
	v_cmp_gt_u32_e64 s[10:11], s48, v66
	s_and_b64 s[10:11], s[8:9], s[10:11]
	s_and_saveexec_b64 s[8:9], s[10:11]
	v_lshl_add_u32 v66, v66, 2, s43
	ds_write_b32 v66, v199
	s_or_b64 exec, exec, s[8:9]
	s_bcnt1_i32_b64 s6, s[6:7]
	s_add_i32 s41, s41, s6
	s_bcnt1_i32_b64 s6, vcc
	s_add_i32 s57, s57, s6
	s_cmpk_lt_i32 s40, 0x1c1
	s_cbranch_scc0 .LBB0_1900

.LBB0_2026:
	v_cmp_gt_u32_e32 vcc, v56, v65
	s_nop 1
	v_cndmask_b32_e64 v66, 0, 1, vcc
	v_cmp_eq_u32_e32 vcc, v56, v65
	s_nop 1
	v_mbcnt_lo_u32_b32 v68, vcc_lo, 0
	v_mbcnt_hi_u32_b32 v67, vcc_hi, v68
	v_add_u32_e32 v67, s57, v67
	v_cmp_gt_u32_e64 s[6:7], s13, v67
	s_nop 1
	v_cndmask_b32_e64 v67, 0, 1, s[6:7]
	v_cndmask_b32_e32 v66, v66, v67, vcc
	v_and_b32_e32 v66, 1, v66
	v_cmp_ne_u32_e64 s[6:7], 0, v66
	v_cmp_eq_u32_e64 s[8:9], 1, v66
	s_nop 0
	v_mbcnt_lo_u32_b32 v67, s6, 0
	v_mbcnt_hi_u32_b32 v66, s7, v67
	v_add_u32_e32 v66, s41, v66
	v_cmp_gt_u32_e64 s[10:11], s48, v66
	s_and_b64 s[10:11], s[8:9], s[10:11]
	s_and_saveexec_b64 s[8:9], s[10:11]
	v_lshl_add_u32 v66, v66, 2, s43
	ds_write_b32 v66, v201
	s_or_b64 exec, exec, s[8:9]
	s_bcnt1_i32_b64 s6, s[6:7]
	s_add_i32 s41, s41, s6
	s_bcnt1_i32_b64 s6, vcc
	s_add_i32 s57, s57, s6
	s_cmpk_lt_i32 s40, 0x241
	s_cbranch_scc0 .LBB0_1904

.LBB0_2030:
	v_cmp_gt_u32_e32 vcc, v54, v65
	s_nop 1
	v_cndmask_b32_e64 v66, 0, 1, vcc
	v_cmp_eq_u32_e32 vcc, v54, v65
	s_nop 1
	v_mbcnt_lo_u32_b32 v68, vcc_lo, 0
	v_mbcnt_hi_u32_b32 v67, vcc_hi, v68
	v_add_u32_e32 v67, s57, v67
	v_cmp_gt_u32_e64 s[6:7], s13, v67
	s_nop 1
	v_cndmask_b32_e64 v67, 0, 1, s[6:7]
	v_cndmask_b32_e32 v66, v66, v67, vcc
	v_and_b32_e32 v66, 1, v66
	v_cmp_ne_u32_e64 s[6:7], 0, v66
	v_cmp_eq_u32_e64 s[8:9], 1, v66
	s_nop 0
	v_mbcnt_lo_u32_b32 v67, s6, 0
	v_mbcnt_hi_u32_b32 v66, s7, v67
	v_add_u32_e32 v66, s41, v66
	v_cmp_gt_u32_e64 s[10:11], s48, v66
	s_and_b64 s[10:11], s[8:9], s[10:11]
	s_and_saveexec_b64 s[8:9], s[10:11]
	v_lshl_add_u32 v66, v66, 2, s43
	ds_write_b32 v66, v203
	s_or_b64 exec, exec, s[8:9]
	s_bcnt1_i32_b64 s6, s[6:7]
	s_add_i32 s41, s41, s6
	s_bcnt1_i32_b64 s6, vcc
	s_add_i32 s57, s57, s6
	s_cmpk_lt_i32 s40, 0x2c1
	s_cbranch_scc0 .LBB0_1908

.LBB0_2034:
	v_cmp_gt_u32_e32 vcc, v52, v65
	s_nop 1
	v_cndmask_b32_e64 v66, 0, 1, vcc
	v_cmp_eq_u32_e32 vcc, v52, v65
	s_nop 1
	v_mbcnt_lo_u32_b32 v68, vcc_lo, 0
	v_mbcnt_hi_u32_b32 v67, vcc_hi, v68
	v_add_u32_e32 v67, s57, v67
	v_cmp_gt_u32_e64 s[6:7], s13, v67
	s_nop 1
	v_cndmask_b32_e64 v67, 0, 1, s[6:7]
	v_cndmask_b32_e32 v66, v66, v67, vcc
	v_and_b32_e32 v66, 1, v66
	v_cmp_ne_u32_e64 s[6:7], 0, v66
	v_cmp_eq_u32_e64 s[8:9], 1, v66
	s_nop 0
	v_mbcnt_lo_u32_b32 v67, s6, 0
	v_mbcnt_hi_u32_b32 v66, s7, v67
	v_add_u32_e32 v66, s41, v66
	v_cmp_gt_u32_e64 s[10:11], s48, v66
	s_and_b64 s[10:11], s[8:9], s[10:11]
	s_and_saveexec_b64 s[8:9], s[10:11]
	v_lshl_add_u32 v66, v66, 2, s43
	ds_write_b32 v66, v205
	s_or_b64 exec, exec, s[8:9]
	s_bcnt1_i32_b64 s6, s[6:7]
	s_add_i32 s41, s41, s6
	s_bcnt1_i32_b64 s6, vcc
	s_add_i32 s57, s57, s6
	s_cmpk_lt_i32 s40, 0x341
	s_cbranch_scc0 .LBB0_1912

.LBB0_2038:
	v_cmp_gt_u32_e32 vcc, v50, v65
	s_nop 1
	v_cndmask_b32_e64 v66, 0, 1, vcc
	v_cmp_eq_u32_e32 vcc, v50, v65
	s_nop 1
	v_mbcnt_lo_u32_b32 v68, vcc_lo, 0
	v_mbcnt_hi_u32_b32 v67, vcc_hi, v68
	v_add_u32_e32 v67, s57, v67
	v_cmp_gt_u32_e64 s[6:7], s13, v67
	s_nop 1
	v_cndmask_b32_e64 v67, 0, 1, s[6:7]
	v_cndmask_b32_e32 v66, v66, v67, vcc
	v_and_b32_e32 v66, 1, v66
	v_cmp_ne_u32_e64 s[6:7], 0, v66
	v_cmp_eq_u32_e64 s[8:9], 1, v66
	s_nop 0
	v_mbcnt_lo_u32_b32 v67, s6, 0
	v_mbcnt_hi_u32_b32 v66, s7, v67
	v_add_u32_e32 v66, s41, v66
	v_cmp_gt_u32_e64 s[10:11], s48, v66
	s_and_b64 s[10:11], s[8:9], s[10:11]
	s_and_saveexec_b64 s[8:9], s[10:11]
	v_lshl_add_u32 v66, v66, 2, s43
	ds_write_b32 v66, v207
	s_or_b64 exec, exec, s[8:9]
	s_bcnt1_i32_b64 s6, s[6:7]
	s_add_i32 s41, s41, s6
	s_bcnt1_i32_b64 s6, vcc
	s_add_i32 s57, s57, s6
	s_cmpk_lt_i32 s40, 0x3c1
	s_cbranch_scc0 .LBB0_1916

.LBB0_2042:
	v_cmp_gt_u32_e32 vcc, v48, v65
	s_nop 1
	v_cndmask_b32_e64 v66, 0, 1, vcc
	v_cmp_eq_u32_e32 vcc, v48, v65
	s_nop 1
	v_mbcnt_lo_u32_b32 v68, vcc_lo, 0
	v_mbcnt_hi_u32_b32 v67, vcc_hi, v68
	v_add_u32_e32 v67, s57, v67
	v_cmp_gt_u32_e64 s[6:7], s13, v67
	s_nop 1
	v_cndmask_b32_e64 v67, 0, 1, s[6:7]
	v_cndmask_b32_e32 v66, v66, v67, vcc
	v_and_b32_e32 v66, 1, v66
	v_cmp_ne_u32_e64 s[6:7], 0, v66
	v_cmp_eq_u32_e64 s[8:9], 1, v66
	s_nop 0
	v_mbcnt_lo_u32_b32 v67, s6, 0
	v_mbcnt_hi_u32_b32 v66, s7, v67
	v_add_u32_e32 v66, s41, v66
	v_cmp_gt_u32_e64 s[10:11], s48, v66
	s_and_b64 s[10:11], s[8:9], s[10:11]
	s_and_saveexec_b64 s[8:9], s[10:11]
	v_lshl_add_u32 v66, v66, 2, s43
	v_or_b32_e32 v67, 0x400, v186
	ds_write_b32 v66, v67
	s_or_b64 exec, exec, s[8:9]
	s_bcnt1_i32_b64 s6, s[6:7]
	s_add_i32 s41, s41, s6
	s_bcnt1_i32_b64 s6, vcc
	s_add_i32 s57, s57, s6
	s_cmpk_lt_i32 s40, 0x441
	s_cbranch_scc0 .LBB0_1920

.LBB0_2046:
	v_cmp_gt_u32_e32 vcc, v46, v65
	s_nop 1
	v_cndmask_b32_e64 v66, 0, 1, vcc
	v_cmp_eq_u32_e32 vcc, v46, v65
	s_nop 1
	v_mbcnt_lo_u32_b32 v68, vcc_lo, 0
	v_mbcnt_hi_u32_b32 v67, vcc_hi, v68
	v_add_u32_e32 v67, s57, v67
	v_cmp_gt_u32_e64 s[6:7], s13, v67
	s_nop 1
	v_cndmask_b32_e64 v67, 0, 1, s[6:7]
	v_cndmask_b32_e32 v66, v66, v67, vcc
	v_and_b32_e32 v66, 1, v66
	v_cmp_ne_u32_e64 s[6:7], 0, v66
	v_cmp_eq_u32_e64 s[8:9], 1, v66
	s_nop 0
	v_mbcnt_lo_u32_b32 v67, s6, 0
	v_mbcnt_hi_u32_b32 v66, s7, v67
	v_add_u32_e32 v66, s41, v66
	v_cmp_gt_u32_e64 s[10:11], s48, v66
	s_and_b64 s[10:11], s[8:9], s[10:11]
	s_and_saveexec_b64 s[8:9], s[10:11]
	v_lshl_add_u32 v66, v66, 2, s43
	v_or_b32_e32 v67, 0x480, v186
	ds_write_b32 v66, v67
	s_or_b64 exec, exec, s[8:9]
	s_bcnt1_i32_b64 s6, s[6:7]
	s_add_i32 s41, s41, s6
	s_bcnt1_i32_b64 s6, vcc
	s_add_i32 s57, s57, s6
	s_cmpk_lt_i32 s40, 0x4c1
	s_cbranch_scc0 .LBB0_1924

.LBB0_2050:
	v_cmp_gt_u32_e32 vcc, v44, v65
	s_nop 1
	v_cndmask_b32_e64 v66, 0, 1, vcc
	v_cmp_eq_u32_e32 vcc, v44, v65
	s_nop 1
	v_mbcnt_lo_u32_b32 v68, vcc_lo, 0
	v_mbcnt_hi_u32_b32 v67, vcc_hi, v68
	v_add_u32_e32 v67, s57, v67
	v_cmp_gt_u32_e64 s[6:7], s13, v67
	s_nop 1
	v_cndmask_b32_e64 v67, 0, 1, s[6:7]
	v_cndmask_b32_e32 v66, v66, v67, vcc
	v_and_b32_e32 v66, 1, v66
	v_cmp_ne_u32_e64 s[6:7], 0, v66
	v_cmp_eq_u32_e64 s[8:9], 1, v66
	s_nop 0
	v_mbcnt_lo_u32_b32 v67, s6, 0
	v_mbcnt_hi_u32_b32 v66, s7, v67
	v_add_u32_e32 v66, s41, v66
	v_cmp_gt_u32_e64 s[10:11], s48, v66
	s_and_b64 s[10:11], s[8:9], s[10:11]
	s_and_saveexec_b64 s[8:9], s[10:11]
	v_lshl_add_u32 v66, v66, 2, s43
	v_or_b32_e32 v67, 0x500, v186
	ds_write_b32 v66, v67
	s_or_b64 exec, exec, s[8:9]
	s_bcnt1_i32_b64 s6, s[6:7]
	s_add_i32 s41, s41, s6
	s_bcnt1_i32_b64 s6, vcc
	s_add_i32 s57, s57, s6
	s_cmpk_lt_i32 s40, 0x541
	s_cbranch_scc0 .LBB0_1928

.LBB0_2054:
	v_cmp_gt_u32_e32 vcc, v42, v65
	s_nop 1
	v_cndmask_b32_e64 v66, 0, 1, vcc
	v_cmp_eq_u32_e32 vcc, v42, v65
	s_nop 1
	v_mbcnt_lo_u32_b32 v68, vcc_lo, 0
	v_mbcnt_hi_u32_b32 v67, vcc_hi, v68
	v_add_u32_e32 v67, s57, v67
	v_cmp_gt_u32_e64 s[6:7], s13, v67
	s_nop 1
	v_cndmask_b32_e64 v67, 0, 1, s[6:7]
	v_cndmask_b32_e32 v66, v66, v67, vcc
	v_and_b32_e32 v66, 1, v66
	v_cmp_ne_u32_e64 s[6:7], 0, v66
	v_cmp_eq_u32_e64 s[8:9], 1, v66
	s_nop 0
	v_mbcnt_lo_u32_b32 v67, s6, 0
	v_mbcnt_hi_u32_b32 v66, s7, v67
	v_add_u32_e32 v66, s41, v66
	v_cmp_gt_u32_e64 s[10:11], s48, v66
	s_and_b64 s[10:11], s[8:9], s[10:11]
	s_and_saveexec_b64 s[8:9], s[10:11]
	v_lshl_add_u32 v66, v66, 2, s43
	v_or_b32_e32 v67, 0x580, v186
	ds_write_b32 v66, v67
	s_or_b64 exec, exec, s[8:9]
	s_bcnt1_i32_b64 s6, s[6:7]
	s_add_i32 s41, s41, s6
	s_bcnt1_i32_b64 s6, vcc
	s_add_i32 s57, s57, s6
	s_cmpk_lt_i32 s40, 0x5c1
	s_cbranch_scc0 .LBB0_1932

.LBB0_2058:
	v_cmp_gt_u32_e32 vcc, v40, v65
	s_nop 1
	v_cndmask_b32_e64 v66, 0, 1, vcc
	v_cmp_eq_u32_e32 vcc, v40, v65
	s_nop 1
	v_mbcnt_lo_u32_b32 v68, vcc_lo, 0
	v_mbcnt_hi_u32_b32 v67, vcc_hi, v68
	v_add_u32_e32 v67, s57, v67
	v_cmp_gt_u32_e64 s[6:7], s13, v67
	s_nop 1
	v_cndmask_b32_e64 v67, 0, 1, s[6:7]
	v_cndmask_b32_e32 v66, v66, v67, vcc
	v_and_b32_e32 v66, 1, v66
	v_cmp_ne_u32_e64 s[6:7], 0, v66
	v_cmp_eq_u32_e64 s[8:9], 1, v66
	s_nop 0
	v_mbcnt_lo_u32_b32 v67, s6, 0
	v_mbcnt_hi_u32_b32 v66, s7, v67
	v_add_u32_e32 v66, s41, v66
	v_cmp_gt_u32_e64 s[10:11], s48, v66
	s_and_b64 s[10:11], s[8:9], s[10:11]
	s_and_saveexec_b64 s[8:9], s[10:11]
	v_lshl_add_u32 v66, v66, 2, s43
	v_or_b32_e32 v67, 0x600, v186
	ds_write_b32 v66, v67
	s_or_b64 exec, exec, s[8:9]
	s_bcnt1_i32_b64 s6, s[6:7]
	s_add_i32 s41, s41, s6
	s_bcnt1_i32_b64 s6, vcc
	s_add_i32 s57, s57, s6
	s_cmpk_lt_i32 s40, 0x641
	s_cbranch_scc0 .LBB0_1936

.LBB0_2062:
	v_cmp_gt_u32_e32 vcc, v38, v65
	s_nop 1
	v_cndmask_b32_e64 v66, 0, 1, vcc
	v_cmp_eq_u32_e32 vcc, v38, v65
	s_nop 1
	v_mbcnt_lo_u32_b32 v68, vcc_lo, 0
	v_mbcnt_hi_u32_b32 v67, vcc_hi, v68
	v_add_u32_e32 v67, s57, v67
	v_cmp_gt_u32_e64 s[6:7], s13, v67
	s_nop 1
	v_cndmask_b32_e64 v67, 0, 1, s[6:7]
	v_cndmask_b32_e32 v66, v66, v67, vcc
	v_and_b32_e32 v66, 1, v66
	v_cmp_ne_u32_e64 s[6:7], 0, v66
	v_cmp_eq_u32_e64 s[8:9], 1, v66
	s_nop 0
	v_mbcnt_lo_u32_b32 v67, s6, 0
	v_mbcnt_hi_u32_b32 v66, s7, v67
	v_add_u32_e32 v66, s41, v66
	v_cmp_gt_u32_e64 s[10:11], s48, v66
	s_and_b64 s[10:11], s[8:9], s[10:11]
	s_and_saveexec_b64 s[8:9], s[10:11]
	v_lshl_add_u32 v66, v66, 2, s43
	v_or_b32_e32 v67, 0x680, v186
	ds_write_b32 v66, v67
	s_or_b64 exec, exec, s[8:9]
	s_bcnt1_i32_b64 s6, s[6:7]
	s_add_i32 s41, s41, s6
	s_bcnt1_i32_b64 s6, vcc
	s_add_i32 s57, s57, s6
	s_cmpk_lt_i32 s40, 0x6c1
	s_cbranch_scc0 .LBB0_1940

.LBB0_2066:
	v_cmp_gt_u32_e32 vcc, v36, v65
	s_nop 1
	v_cndmask_b32_e64 v66, 0, 1, vcc
	v_cmp_eq_u32_e32 vcc, v36, v65
	s_nop 1
	v_mbcnt_lo_u32_b32 v68, vcc_lo, 0
	v_mbcnt_hi_u32_b32 v67, vcc_hi, v68
	v_add_u32_e32 v67, s57, v67
	v_cmp_gt_u32_e64 s[6:7], s13, v67
	s_nop 1
	v_cndmask_b32_e64 v67, 0, 1, s[6:7]
	v_cndmask_b32_e32 v66, v66, v67, vcc
	v_and_b32_e32 v66, 1, v66
	v_cmp_ne_u32_e64 s[6:7], 0, v66
	v_cmp_eq_u32_e64 s[8:9], 1, v66
	s_nop 0
	v_mbcnt_lo_u32_b32 v67, s6, 0
	v_mbcnt_hi_u32_b32 v66, s7, v67
	v_add_u32_e32 v66, s41, v66
	v_cmp_gt_u32_e64 s[10:11], s48, v66
	s_and_b64 s[10:11], s[8:9], s[10:11]
	s_and_saveexec_b64 s[8:9], s[10:11]
	v_lshl_add_u32 v66, v66, 2, s43
	v_or_b32_e32 v67, 0x700, v186
	ds_write_b32 v66, v67
	s_or_b64 exec, exec, s[8:9]
	s_bcnt1_i32_b64 s6, s[6:7]
	s_add_i32 s41, s41, s6
	s_bcnt1_i32_b64 s6, vcc
	s_add_i32 s57, s57, s6
	s_cmpk_lt_i32 s40, 0x741
	s_cbranch_scc0 .LBB0_1944

.LBB0_2070:
	v_cmp_gt_u32_e32 vcc, v34, v65
	s_nop 1
	v_cndmask_b32_e64 v66, 0, 1, vcc
	v_cmp_eq_u32_e32 vcc, v34, v65
	s_nop 1
	v_mbcnt_lo_u32_b32 v68, vcc_lo, 0
	v_mbcnt_hi_u32_b32 v67, vcc_hi, v68
	v_add_u32_e32 v67, s57, v67
	v_cmp_gt_u32_e64 s[6:7], s13, v67
	s_nop 1
	v_cndmask_b32_e64 v67, 0, 1, s[6:7]
	v_cndmask_b32_e32 v66, v66, v67, vcc
	v_and_b32_e32 v66, 1, v66
	v_cmp_ne_u32_e64 s[6:7], 0, v66
	v_cmp_eq_u32_e64 s[8:9], 1, v66
	s_nop 0
	v_mbcnt_lo_u32_b32 v67, s6, 0
	v_mbcnt_hi_u32_b32 v66, s7, v67
	v_add_u32_e32 v66, s41, v66
	v_cmp_gt_u32_e64 s[10:11], s48, v66
	s_and_b64 s[10:11], s[8:9], s[10:11]
	s_and_saveexec_b64 s[8:9], s[10:11]
	v_lshl_add_u32 v66, v66, 2, s43
	v_or_b32_e32 v67, 0x780, v186
	ds_write_b32 v66, v67
	s_or_b64 exec, exec, s[8:9]
	s_bcnt1_i32_b64 s6, s[6:7]
	s_add_i32 s41, s41, s6
	s_bcnt1_i32_b64 s6, vcc
	s_add_i32 s57, s57, s6
	s_cmpk_lt_i32 s40, 0x7c1
	s_cbranch_scc0 .LBB0_1948

.LBB0_2074:
	v_cmp_gt_u32_e32 vcc, v32, v65
	s_nop 1
	v_cndmask_b32_e64 v66, 0, 1, vcc
	v_cmp_eq_u32_e32 vcc, v32, v65
	s_nop 1
	v_mbcnt_lo_u32_b32 v68, vcc_lo, 0
	v_mbcnt_hi_u32_b32 v67, vcc_hi, v68
	v_add_u32_e32 v67, s57, v67
	v_cmp_gt_u32_e64 s[6:7], s13, v67
	s_nop 1
	v_cndmask_b32_e64 v67, 0, 1, s[6:7]
	v_cndmask_b32_e32 v66, v66, v67, vcc
	v_and_b32_e32 v66, 1, v66
	v_cmp_ne_u32_e64 s[6:7], 0, v66
	v_cmp_eq_u32_e64 s[8:9], 1, v66
	s_nop 0
	v_mbcnt_lo_u32_b32 v67, s6, 0
	v_mbcnt_hi_u32_b32 v66, s7, v67
	v_add_u32_e32 v66, s41, v66
	v_cmp_gt_u32_e64 s[10:11], s48, v66
	s_and_b64 s[10:11], s[8:9], s[10:11]
	s_and_saveexec_b64 s[8:9], s[10:11]
	v_lshl_add_u32 v66, v66, 2, s43
	v_or_b32_e32 v67, 0x800, v186
	ds_write_b32 v66, v67
	s_or_b64 exec, exec, s[8:9]
	s_bcnt1_i32_b64 s6, s[6:7]
	s_add_i32 s41, s41, s6
	s_bcnt1_i32_b64 s6, vcc
	s_add_i32 s57, s57, s6
	s_cmpk_lt_i32 s40, 0x841
	s_cbranch_scc0 .LBB0_1952

.LBB0_2078:
	v_cmp_gt_u32_e32 vcc, v30, v65
	s_nop 1
	v_cndmask_b32_e64 v66, 0, 1, vcc
	v_cmp_eq_u32_e32 vcc, v30, v65
	s_nop 1
	v_mbcnt_lo_u32_b32 v68, vcc_lo, 0
	v_mbcnt_hi_u32_b32 v67, vcc_hi, v68
	v_add_u32_e32 v67, s57, v67
	v_cmp_gt_u32_e64 s[6:7], s13, v67
	s_nop 1
	v_cndmask_b32_e64 v67, 0, 1, s[6:7]
	v_cndmask_b32_e32 v66, v66, v67, vcc
	v_and_b32_e32 v66, 1, v66
	v_cmp_ne_u32_e64 s[6:7], 0, v66
	v_cmp_eq_u32_e64 s[8:9], 1, v66
	s_nop 0
	v_mbcnt_lo_u32_b32 v67, s6, 0
	v_mbcnt_hi_u32_b32 v66, s7, v67
	v_add_u32_e32 v66, s41, v66
	v_cmp_gt_u32_e64 s[10:11], s48, v66
	s_and_b64 s[10:11], s[8:9], s[10:11]
	s_and_saveexec_b64 s[8:9], s[10:11]
	v_lshl_add_u32 v66, v66, 2, s43
	v_or_b32_e32 v67, 0x880, v186
	ds_write_b32 v66, v67
	s_or_b64 exec, exec, s[8:9]
	s_bcnt1_i32_b64 s6, s[6:7]
	s_add_i32 s41, s41, s6
	s_bcnt1_i32_b64 s6, vcc
	s_add_i32 s57, s57, s6
	s_cmpk_lt_i32 s40, 0x8c1
	s_cbranch_scc0 .LBB0_1956

.LBB0_2082:
	v_cmp_gt_u32_e32 vcc, v28, v65
	s_nop 1
	v_cndmask_b32_e64 v66, 0, 1, vcc
	v_cmp_eq_u32_e32 vcc, v28, v65
	s_nop 1
	v_mbcnt_lo_u32_b32 v68, vcc_lo, 0
	v_mbcnt_hi_u32_b32 v67, vcc_hi, v68
	v_add_u32_e32 v67, s57, v67
	v_cmp_gt_u32_e64 s[6:7], s13, v67
	s_nop 1
	v_cndmask_b32_e64 v67, 0, 1, s[6:7]
	v_cndmask_b32_e32 v66, v66, v67, vcc
	v_and_b32_e32 v66, 1, v66
	v_cmp_ne_u32_e64 s[6:7], 0, v66
	v_cmp_eq_u32_e64 s[8:9], 1, v66
	s_nop 0
	v_mbcnt_lo_u32_b32 v67, s6, 0
	v_mbcnt_hi_u32_b32 v66, s7, v67
	v_add_u32_e32 v66, s41, v66
	v_cmp_gt_u32_e64 s[10:11], s48, v66
	s_and_b64 s[10:11], s[8:9], s[10:11]
	s_and_saveexec_b64 s[8:9], s[10:11]
	v_lshl_add_u32 v66, v66, 2, s43
	v_or_b32_e32 v67, 0x900, v186
	ds_write_b32 v66, v67
	s_or_b64 exec, exec, s[8:9]
	s_bcnt1_i32_b64 s6, s[6:7]
	s_add_i32 s41, s41, s6
	s_bcnt1_i32_b64 s6, vcc
	s_add_i32 s57, s57, s6
	s_cmpk_lt_i32 s40, 0x941
	s_cbranch_scc0 .LBB0_1960

.LBB0_2086:
	v_cmp_gt_u32_e32 vcc, v26, v65
	s_nop 1
	v_cndmask_b32_e64 v66, 0, 1, vcc
	v_cmp_eq_u32_e32 vcc, v26, v65
	s_nop 1
	v_mbcnt_lo_u32_b32 v68, vcc_lo, 0
	v_mbcnt_hi_u32_b32 v67, vcc_hi, v68
	v_add_u32_e32 v67, s57, v67
	v_cmp_gt_u32_e64 s[6:7], s13, v67
	s_nop 1
	v_cndmask_b32_e64 v67, 0, 1, s[6:7]
	v_cndmask_b32_e32 v66, v66, v67, vcc
	v_and_b32_e32 v66, 1, v66
	v_cmp_ne_u32_e64 s[6:7], 0, v66
	v_cmp_eq_u32_e64 s[8:9], 1, v66
	s_nop 0
	v_mbcnt_lo_u32_b32 v67, s6, 0
	v_mbcnt_hi_u32_b32 v66, s7, v67
	v_add_u32_e32 v66, s41, v66
	v_cmp_gt_u32_e64 s[10:11], s48, v66
	s_and_b64 s[10:11], s[8:9], s[10:11]
	s_and_saveexec_b64 s[8:9], s[10:11]
	v_lshl_add_u32 v66, v66, 2, s43
	v_or_b32_e32 v67, 0x980, v186
	ds_write_b32 v66, v67
	s_or_b64 exec, exec, s[8:9]
	s_bcnt1_i32_b64 s6, s[6:7]
	s_add_i32 s41, s41, s6
	s_bcnt1_i32_b64 s6, vcc
	s_add_i32 s57, s57, s6
	s_cmpk_lt_i32 s40, 0x9c1
	s_cbranch_scc0 .LBB0_1964

.LBB0_2090:
	v_cmp_gt_u32_e32 vcc, v24, v65
	s_nop 1
	v_cndmask_b32_e64 v66, 0, 1, vcc
	v_cmp_eq_u32_e32 vcc, v24, v65
	s_nop 1
	v_mbcnt_lo_u32_b32 v68, vcc_lo, 0
	v_mbcnt_hi_u32_b32 v67, vcc_hi, v68
	v_add_u32_e32 v67, s57, v67
	v_cmp_gt_u32_e64 s[6:7], s13, v67
	s_nop 1
	v_cndmask_b32_e64 v67, 0, 1, s[6:7]
	v_cndmask_b32_e32 v66, v66, v67, vcc
	v_and_b32_e32 v66, 1, v66
	v_cmp_ne_u32_e64 s[6:7], 0, v66
	v_cmp_eq_u32_e64 s[8:9], 1, v66
	s_nop 0
	v_mbcnt_lo_u32_b32 v67, s6, 0
	v_mbcnt_hi_u32_b32 v66, s7, v67
	v_add_u32_e32 v66, s41, v66
	v_cmp_gt_u32_e64 s[10:11], s48, v66
	s_and_b64 s[10:11], s[8:9], s[10:11]
	s_and_saveexec_b64 s[8:9], s[10:11]
	v_lshl_add_u32 v66, v66, 2, s43
	v_or_b32_e32 v67, 0xa00, v186
	ds_write_b32 v66, v67
	s_or_b64 exec, exec, s[8:9]
	s_bcnt1_i32_b64 s6, s[6:7]
	s_add_i32 s41, s41, s6
	s_bcnt1_i32_b64 s6, vcc
	s_add_i32 s57, s57, s6
	s_cmpk_lt_i32 s40, 0xa41
	s_cbranch_scc0 .LBB0_1968

.LBB0_2094:
	v_cmp_gt_u32_e32 vcc, v22, v65
	s_nop 1
	v_cndmask_b32_e64 v66, 0, 1, vcc
	v_cmp_eq_u32_e32 vcc, v22, v65
	s_nop 1
	v_mbcnt_lo_u32_b32 v68, vcc_lo, 0
	v_mbcnt_hi_u32_b32 v67, vcc_hi, v68
	v_add_u32_e32 v67, s57, v67
	v_cmp_gt_u32_e64 s[6:7], s13, v67
	s_nop 1
	v_cndmask_b32_e64 v67, 0, 1, s[6:7]
	v_cndmask_b32_e32 v66, v66, v67, vcc
	v_and_b32_e32 v66, 1, v66
	v_cmp_ne_u32_e64 s[6:7], 0, v66
	v_cmp_eq_u32_e64 s[8:9], 1, v66
	s_nop 0
	v_mbcnt_lo_u32_b32 v67, s6, 0
	v_mbcnt_hi_u32_b32 v66, s7, v67
	v_add_u32_e32 v66, s41, v66
	v_cmp_gt_u32_e64 s[10:11], s48, v66
	s_and_b64 s[10:11], s[8:9], s[10:11]
	s_and_saveexec_b64 s[8:9], s[10:11]
	v_lshl_add_u32 v66, v66, 2, s43
	v_or_b32_e32 v67, 0xa80, v186
	ds_write_b32 v66, v67
	s_or_b64 exec, exec, s[8:9]
	s_bcnt1_i32_b64 s6, s[6:7]
	s_add_i32 s41, s41, s6
	s_bcnt1_i32_b64 s6, vcc
	s_add_i32 s57, s57, s6
	s_cmpk_lt_i32 s40, 0xac1
	s_cbranch_scc0 .LBB0_1972

.LBB0_2098:
	v_cmp_gt_u32_e32 vcc, v20, v65
	s_nop 1
	v_cndmask_b32_e64 v66, 0, 1, vcc
	v_cmp_eq_u32_e32 vcc, v20, v65
	s_nop 1
	v_mbcnt_lo_u32_b32 v68, vcc_lo, 0
	v_mbcnt_hi_u32_b32 v67, vcc_hi, v68
	v_add_u32_e32 v67, s57, v67
	v_cmp_gt_u32_e64 s[6:7], s13, v67
	s_nop 1
	v_cndmask_b32_e64 v67, 0, 1, s[6:7]
	v_cndmask_b32_e32 v66, v66, v67, vcc
	v_and_b32_e32 v66, 1, v66
	v_cmp_ne_u32_e64 s[6:7], 0, v66
	v_cmp_eq_u32_e64 s[8:9], 1, v66
	s_nop 0
	v_mbcnt_lo_u32_b32 v67, s6, 0
	v_mbcnt_hi_u32_b32 v66, s7, v67
	v_add_u32_e32 v66, s41, v66
	v_cmp_gt_u32_e64 s[10:11], s48, v66
	s_and_b64 s[10:11], s[8:9], s[10:11]
	s_and_saveexec_b64 s[8:9], s[10:11]
	v_lshl_add_u32 v66, v66, 2, s43
	v_or_b32_e32 v67, 0xb00, v186
	ds_write_b32 v66, v67
	s_or_b64 exec, exec, s[8:9]
	s_bcnt1_i32_b64 s6, s[6:7]
	s_add_i32 s41, s41, s6
	s_bcnt1_i32_b64 s6, vcc
	s_add_i32 s57, s57, s6
	s_cmpk_lt_i32 s40, 0xb41
	s_cbranch_scc0 .LBB0_1976

.LBB0_2102:
	v_cmp_gt_u32_e32 vcc, v18, v65
	s_nop 1
	v_cndmask_b32_e64 v66, 0, 1, vcc
	v_cmp_eq_u32_e32 vcc, v18, v65
	s_nop 1
	v_mbcnt_lo_u32_b32 v68, vcc_lo, 0
	v_mbcnt_hi_u32_b32 v67, vcc_hi, v68
	v_add_u32_e32 v67, s57, v67
	v_cmp_gt_u32_e64 s[6:7], s13, v67
	s_nop 1
	v_cndmask_b32_e64 v67, 0, 1, s[6:7]
	v_cndmask_b32_e32 v66, v66, v67, vcc
	v_and_b32_e32 v66, 1, v66
	v_cmp_ne_u32_e64 s[6:7], 0, v66
	v_cmp_eq_u32_e64 s[8:9], 1, v66
	s_nop 0
	v_mbcnt_lo_u32_b32 v67, s6, 0
	v_mbcnt_hi_u32_b32 v66, s7, v67
	v_add_u32_e32 v66, s41, v66
	v_cmp_gt_u32_e64 s[10:11], s48, v66
	s_and_b64 s[10:11], s[8:9], s[10:11]
	s_and_saveexec_b64 s[8:9], s[10:11]
	v_lshl_add_u32 v66, v66, 2, s43
	v_or_b32_e32 v67, 0xb80, v186
	ds_write_b32 v66, v67
	s_or_b64 exec, exec, s[8:9]
	s_bcnt1_i32_b64 s6, s[6:7]
	s_add_i32 s41, s41, s6
	s_bcnt1_i32_b64 s6, vcc
	s_add_i32 s57, s57, s6
	s_cmpk_lt_i32 s40, 0xbc1
	s_cbranch_scc0 .LBB0_1980

.LBB0_2106:
	v_cmp_gt_u32_e32 vcc, v16, v65
	s_nop 1
	v_cndmask_b32_e64 v66, 0, 1, vcc
	v_cmp_eq_u32_e32 vcc, v16, v65
	s_nop 1
	v_mbcnt_lo_u32_b32 v68, vcc_lo, 0
	v_mbcnt_hi_u32_b32 v67, vcc_hi, v68
	v_add_u32_e32 v67, s57, v67
	v_cmp_gt_u32_e64 s[6:7], s13, v67
	s_nop 1
	v_cndmask_b32_e64 v67, 0, 1, s[6:7]
	v_cndmask_b32_e32 v66, v66, v67, vcc
	v_and_b32_e32 v66, 1, v66
	v_cmp_ne_u32_e64 s[6:7], 0, v66
	v_cmp_eq_u32_e64 s[8:9], 1, v66
	s_nop 0
	v_mbcnt_lo_u32_b32 v67, s6, 0
	v_mbcnt_hi_u32_b32 v66, s7, v67
	v_add_u32_e32 v66, s41, v66
	v_cmp_gt_u32_e64 s[10:11], s48, v66
	s_and_b64 s[10:11], s[8:9], s[10:11]
	s_and_saveexec_b64 s[8:9], s[10:11]
	v_lshl_add_u32 v66, v66, 2, s43
	v_or_b32_e32 v67, 0xc00, v186
	ds_write_b32 v66, v67
	s_or_b64 exec, exec, s[8:9]
	s_bcnt1_i32_b64 s6, s[6:7]
	s_add_i32 s41, s41, s6
	s_bcnt1_i32_b64 s6, vcc
	s_add_i32 s57, s57, s6
	s_cmpk_lt_i32 s40, 0xc41
	s_cbranch_scc0 .LBB0_1984

.LBB0_2110:
	v_cmp_gt_u32_e32 vcc, v14, v65
	s_nop 1
	v_cndmask_b32_e64 v66, 0, 1, vcc
	v_cmp_eq_u32_e32 vcc, v14, v65
	s_nop 1
	v_mbcnt_lo_u32_b32 v68, vcc_lo, 0
	v_mbcnt_hi_u32_b32 v67, vcc_hi, v68
	v_add_u32_e32 v67, s57, v67
	v_cmp_gt_u32_e64 s[6:7], s13, v67
	s_nop 1
	v_cndmask_b32_e64 v67, 0, 1, s[6:7]
	v_cndmask_b32_e32 v66, v66, v67, vcc
	v_and_b32_e32 v66, 1, v66
	v_cmp_ne_u32_e64 s[6:7], 0, v66
	v_cmp_eq_u32_e64 s[8:9], 1, v66
	s_nop 0
	v_mbcnt_lo_u32_b32 v67, s6, 0
	v_mbcnt_hi_u32_b32 v66, s7, v67
	v_add_u32_e32 v66, s41, v66
	v_cmp_gt_u32_e64 s[10:11], s48, v66
	s_and_b64 s[10:11], s[8:9], s[10:11]
	s_and_saveexec_b64 s[8:9], s[10:11]
	v_lshl_add_u32 v66, v66, 2, s43
	ds_write_b32 v66, v240
	s_or_b64 exec, exec, s[8:9]
	s_bcnt1_i32_b64 s6, s[6:7]
	s_add_i32 s41, s41, s6
	s_bcnt1_i32_b64 s6, vcc
	s_add_i32 s57, s57, s6
	s_cmpk_lt_i32 s40, 0xcc1
	s_cbranch_scc0 .LBB0_1988

.LBB0_2114:
	v_cmp_gt_u32_e32 vcc, v12, v65
	s_nop 1
	v_cndmask_b32_e64 v66, 0, 1, vcc
	v_cmp_eq_u32_e32 vcc, v12, v65
	s_nop 1
	v_mbcnt_lo_u32_b32 v68, vcc_lo, 0
	v_mbcnt_hi_u32_b32 v67, vcc_hi, v68
	v_add_u32_e32 v67, s57, v67
	v_cmp_gt_u32_e64 s[6:7], s13, v67
	s_nop 1
	v_cndmask_b32_e64 v67, 0, 1, s[6:7]
	v_cndmask_b32_e32 v66, v66, v67, vcc
	v_and_b32_e32 v66, 1, v66
	v_cmp_ne_u32_e64 s[6:7], 0, v66
	v_cmp_eq_u32_e64 s[8:9], 1, v66
	s_nop 0
	v_mbcnt_lo_u32_b32 v67, s6, 0
	v_mbcnt_hi_u32_b32 v66, s7, v67
	v_add_u32_e32 v66, s41, v66
	v_cmp_gt_u32_e64 s[10:11], s48, v66
	s_and_b64 s[10:11], s[8:9], s[10:11]
	s_and_saveexec_b64 s[8:9], s[10:11]
	v_lshl_add_u32 v66, v66, 2, s43
	ds_write_b32 v66, v246
	s_or_b64 exec, exec, s[8:9]
	s_bcnt1_i32_b64 s6, s[6:7]
	s_add_i32 s41, s41, s6
	s_bcnt1_i32_b64 s6, vcc
	s_add_i32 s57, s57, s6
	s_cmpk_lt_i32 s40, 0xd41
	s_cbranch_scc0 .LBB0_1992

.LBB0_2118:
	v_cmp_gt_u32_e32 vcc, v10, v65
	s_nop 1
	v_cndmask_b32_e64 v66, 0, 1, vcc
	v_cmp_eq_u32_e32 vcc, v10, v65
	s_nop 1
	v_mbcnt_lo_u32_b32 v68, vcc_lo, 0
	v_mbcnt_hi_u32_b32 v67, vcc_hi, v68
	v_add_u32_e32 v67, s57, v67
	v_cmp_gt_u32_e64 s[6:7], s13, v67
	s_nop 1
	v_cndmask_b32_e64 v67, 0, 1, s[6:7]
	v_cndmask_b32_e32 v66, v66, v67, vcc
	v_and_b32_e32 v66, 1, v66
	v_cmp_ne_u32_e64 s[6:7], 0, v66
	v_cmp_eq_u32_e64 s[8:9], 1, v66
	s_nop 0
	v_mbcnt_lo_u32_b32 v67, s6, 0
	v_mbcnt_hi_u32_b32 v66, s7, v67
	v_add_u32_e32 v66, s41, v66
	v_cmp_gt_u32_e64 s[10:11], s48, v66
	s_and_b64 s[10:11], s[8:9], s[10:11]
	s_and_saveexec_b64 s[8:9], s[10:11]
	v_lshl_add_u32 v66, v66, 2, s43
	ds_write_b32 v66, v248
	s_or_b64 exec, exec, s[8:9]
	s_bcnt1_i32_b64 s6, s[6:7]
	s_add_i32 s41, s41, s6
	s_bcnt1_i32_b64 s6, vcc
	s_add_i32 s57, s57, s6
	s_cmpk_lt_i32 s40, 0xdc1
	s_cbranch_scc0 .LBB0_1996

.LBB0_2122:
	v_cmp_gt_u32_e32 vcc, v8, v65
	s_nop 1
	v_cndmask_b32_e64 v66, 0, 1, vcc
	v_cmp_eq_u32_e32 vcc, v8, v65
	s_nop 1
	v_mbcnt_lo_u32_b32 v68, vcc_lo, 0
	v_mbcnt_hi_u32_b32 v67, vcc_hi, v68
	v_add_u32_e32 v67, s57, v67
	v_cmp_gt_u32_e64 s[6:7], s13, v67
	s_nop 1
	v_cndmask_b32_e64 v67, 0, 1, s[6:7]
	v_cndmask_b32_e32 v66, v66, v67, vcc
	v_and_b32_e32 v66, 1, v66
	v_cmp_ne_u32_e64 s[6:7], 0, v66
	v_cmp_eq_u32_e64 s[8:9], 1, v66
	s_nop 0
	v_mbcnt_lo_u32_b32 v67, s6, 0
	v_mbcnt_hi_u32_b32 v66, s7, v67
	v_add_u32_e32 v66, s41, v66
	v_cmp_gt_u32_e64 s[10:11], s48, v66
	s_and_b64 s[10:11], s[8:9], s[10:11]
	s_and_saveexec_b64 s[8:9], s[10:11]
	v_lshl_add_u32 v66, v66, 2, s43
	ds_write_b32 v66, v250
	s_or_b64 exec, exec, s[8:9]
	s_bcnt1_i32_b64 s6, s[6:7]
	s_add_i32 s41, s41, s6
	s_bcnt1_i32_b64 s6, vcc
	s_add_i32 s57, s57, s6
	s_cmpk_lt_i32 s40, 0xe41
	s_cbranch_scc0 .LBB0_2000

.LBB0_2126:
	v_cmp_gt_u32_e32 vcc, v6, v65
	s_nop 1
	v_cndmask_b32_e64 v66, 0, 1, vcc
	v_cmp_eq_u32_e32 vcc, v6, v65
	s_nop 1
	v_mbcnt_lo_u32_b32 v68, vcc_lo, 0
	v_mbcnt_hi_u32_b32 v67, vcc_hi, v68
	v_add_u32_e32 v67, s57, v67
	v_cmp_gt_u32_e64 s[6:7], s13, v67
	s_nop 1
	v_cndmask_b32_e64 v67, 0, 1, s[6:7]
	v_cndmask_b32_e32 v66, v66, v67, vcc
	v_and_b32_e32 v66, 1, v66
	v_cmp_ne_u32_e64 s[6:7], 0, v66
	v_cmp_eq_u32_e64 s[8:9], 1, v66
	s_nop 0
	v_mbcnt_lo_u32_b32 v67, s6, 0
	v_mbcnt_hi_u32_b32 v66, s7, v67
	v_add_u32_e32 v66, s41, v66
	v_cmp_gt_u32_e64 s[10:11], s48, v66
	s_and_b64 s[10:11], s[8:9], s[10:11]
	s_and_saveexec_b64 s[8:9], s[10:11]
	v_lshl_add_u32 v66, v66, 2, s43
	ds_write_b32 v66, v252
	s_or_b64 exec, exec, s[8:9]
	s_bcnt1_i32_b64 s6, s[6:7]
	s_add_i32 s41, s41, s6
	s_bcnt1_i32_b64 s6, vcc
	s_add_i32 s57, s57, s6
	s_cmpk_lt_i32 s40, 0xec1
	s_cbranch_scc0 .LBB0_2004

.LBB0_2130:
	v_cmp_gt_u32_e32 vcc, v4, v65
	s_nop 1
	v_cndmask_b32_e64 v66, 0, 1, vcc
	v_cmp_eq_u32_e32 vcc, v4, v65
	s_nop 1
	v_mbcnt_lo_u32_b32 v68, vcc_lo, 0
	v_mbcnt_hi_u32_b32 v67, vcc_hi, v68
	v_add_u32_e32 v67, s57, v67
	v_cmp_gt_u32_e64 s[6:7], s13, v67
	s_nop 1
	v_cndmask_b32_e64 v67, 0, 1, s[6:7]
	v_cndmask_b32_e32 v66, v66, v67, vcc
	v_and_b32_e32 v66, 1, v66
	v_cmp_ne_u32_e64 s[6:7], 0, v66
	v_cmp_eq_u32_e64 s[8:9], 1, v66
	s_nop 0
	v_mbcnt_lo_u32_b32 v67, s6, 0
	v_mbcnt_hi_u32_b32 v66, s7, v67
	v_add_u32_e32 v66, s41, v66
	v_cmp_gt_u32_e64 s[10:11], s48, v66
	s_and_b64 s[10:11], s[8:9], s[10:11]
	s_and_saveexec_b64 s[8:9], s[10:11]
	v_lshl_add_u32 v66, v66, 2, s43
	ds_write_b32 v66, v254
	s_or_b64 exec, exec, s[8:9]
	s_bcnt1_i32_b64 s6, s[6:7]
	s_add_i32 s41, s41, s6
	s_bcnt1_i32_b64 s6, vcc
	s_add_i32 s57, s57, s6
	s_cmpk_lt_i32 s40, 0xf41
	s_cbranch_scc0 .LBB0_2008

.LBB0_2134:
	v_cmp_gt_u32_e32 vcc, v2, v65
	s_nop 1
	v_cndmask_b32_e64 v66, 0, 1, vcc
	v_cmp_eq_u32_e32 vcc, v2, v65
	s_nop 1
	v_mbcnt_lo_u32_b32 v68, vcc_lo, 0
	v_mbcnt_hi_u32_b32 v67, vcc_hi, v68
	v_add_u32_e32 v67, s57, v67
	v_cmp_gt_u32_e64 s[6:7], s13, v67
	s_nop 1
	v_cndmask_b32_e64 v67, 0, 1, s[6:7]
	v_cndmask_b32_e32 v66, v66, v67, vcc
	v_and_b32_e32 v66, 1, v66
	v_cmp_ne_u32_e64 s[6:7], 0, v66
	v_cmp_eq_u32_e64 s[8:9], 1, v66
	s_nop 0
	v_mbcnt_lo_u32_b32 v67, s6, 0
	v_mbcnt_hi_u32_b32 v66, s7, v67
	v_add_u32_e32 v66, s41, v66
	v_cmp_gt_u32_e64 s[10:11], s48, v66
	s_and_b64 s[10:11], s[8:9], s[10:11]
	s_and_saveexec_b64 s[8:9], s[10:11]
	v_lshl_add_u32 v66, v66, 2, s43
	ds_write_b32 v66, v210
	s_or_b64 exec, exec, s[8:9]
	s_bcnt1_i32_b64 s6, s[6:7]
	s_add_i32 s41, s41, s6
	s_bcnt1_i32_b64 s6, vcc
	s_add_i32 s57, s57, s6
	s_cmpk_lt_i32 s40, 0xfc1
	s_cbranch_scc1 .LBB0_2140
.LBB0_2137:
	v_cmp_gt_u32_e32 vcc, v0, v65
	s_nop 1
	v_cndmask_b32_e64 v66, 0, 1, vcc
	v_cmp_eq_u32_e32 vcc, v0, v65
	s_nop 1
	v_mbcnt_lo_u32_b32 v67, vcc_lo, 0
	v_mbcnt_hi_u32_b32 v65, vcc_hi, v67
	v_add_u32_e32 v65, s57, v65
	v_cmp_gt_u32_e64 s[6:7], s13, v65
	s_nop 1
	v_cndmask_b32_e64 v65, 0, 1, s[6:7]
	v_cndmask_b32_e32 v65, v66, v65, vcc
	v_and_b32_e32 v65, 1, v65
	v_cmp_ne_u32_e64 s[6:7], 0, v65
	v_cmp_eq_u32_e32 vcc, 1, v65
	s_nop 0
	v_mbcnt_lo_u32_b32 v66, s6, 0
	v_mbcnt_hi_u32_b32 v65, s7, v66
	v_add_u32_e32 v65, s41, v65
	v_cmp_gt_u32_e64 s[6:7], s48, v65
	s_and_b64 s[8:9], vcc, s[6:7]
	s_and_saveexec_b64 s[6:7], s[8:9]
	v_lshl_add_u32 v65, v65, 2, s43
	ds_write_b32 v65, v211
	s_or_b64 exec, exec, s[6:7]

.LBB0_2141:
	s_and_b64 vcc, exec, s[6:7]
	s_cbranch_vccz .LBB0_2484
	s_cmp_lt_i32 s12, 1
	s_cbranch_scc1 .LBB0_2270
	v_cmp_ge_u32_e32 vcc, v64, v223
	s_and_saveexec_b64 s[6:7], vcc
	s_cbranch_execz .LBB0_2145
	v_mbcnt_lo_u32_b32 v66, vcc_lo, 0
	v_mbcnt_hi_u32_b32 v65, vcc_hi, v66
	v_lshl_add_u32 v65, v65, 2, s3
	ds_write2st64_b32 v65, v64, v186 offset1:16

.LBB0_2146:
	v_cmp_ge_u32_e32 vcc, v63, v223
	s_and_saveexec_b64 s[6:7], vcc
	s_cbranch_execz .LBB0_2148
	v_mbcnt_lo_u32_b32 v65, vcc_lo, 0
	v_mbcnt_hi_u32_b32 v64, vcc_hi, v65
	v_add_u32_e32 v64, s8, v64
	v_lshl_add_u32 v64, v64, 2, s3
	ds_write2st64_b32 v64, v63, v194 offset1:16

.LBB0_2150:
	v_cmp_ge_u32_e32 vcc, v61, v223
	s_and_saveexec_b64 s[6:7], vcc
	s_cbranch_execz .LBB0_2152
	v_mbcnt_lo_u32_b32 v63, vcc_lo, 0
	v_mbcnt_hi_u32_b32 v62, vcc_hi, v63
	v_add_u32_e32 v62, s8, v62
	v_lshl_add_u32 v62, v62, 2, s3
	ds_write2st64_b32 v62, v61, v196 offset1:16

.LBB0_2154:
	v_cmp_ge_u32_e32 vcc, v59, v223
	s_and_saveexec_b64 s[6:7], vcc
	s_cbranch_execz .LBB0_2156
	v_mbcnt_lo_u32_b32 v61, vcc_lo, 0
	v_mbcnt_hi_u32_b32 v60, vcc_hi, v61
	v_add_u32_e32 v60, s8, v60
	v_lshl_add_u32 v60, v60, 2, s3
	ds_write2st64_b32 v60, v59, v198 offset1:16

.LBB0_2158:
	v_cmp_ge_u32_e32 vcc, v57, v223
	s_and_saveexec_b64 s[6:7], vcc
	s_cbranch_execz .LBB0_2160
	v_mbcnt_lo_u32_b32 v59, vcc_lo, 0
	v_mbcnt_hi_u32_b32 v58, vcc_hi, v59
	v_add_u32_e32 v58, s8, v58
	v_lshl_add_u32 v58, v58, 2, s3
	ds_write2st64_b32 v58, v57, v200 offset1:16

.LBB0_2162:
	v_cmp_ge_u32_e32 vcc, v55, v223
	s_and_saveexec_b64 s[6:7], vcc
	s_cbranch_execz .LBB0_2164
	v_mbcnt_lo_u32_b32 v57, vcc_lo, 0
	v_mbcnt_hi_u32_b32 v56, vcc_hi, v57
	v_add_u32_e32 v56, s8, v56
	v_lshl_add_u32 v56, v56, 2, s3
	ds_write2st64_b32 v56, v55, v202 offset1:16

.LBB0_2166:
	v_cmp_ge_u32_e32 vcc, v53, v223
	s_and_saveexec_b64 s[6:7], vcc
	s_cbranch_execz .LBB0_2168
	v_mbcnt_lo_u32_b32 v55, vcc_lo, 0
	v_mbcnt_hi_u32_b32 v54, vcc_hi, v55
	v_add_u32_e32 v54, s8, v54
	v_lshl_add_u32 v54, v54, 2, s3
	ds_write2st64_b32 v54, v53, v204 offset1:16

.LBB0_2170:
	v_cmp_ge_u32_e32 vcc, v51, v223
	s_and_saveexec_b64 s[6:7], vcc
	s_cbranch_execz .LBB0_2172
	v_mbcnt_lo_u32_b32 v53, vcc_lo, 0
	v_mbcnt_hi_u32_b32 v52, vcc_hi, v53
	v_add_u32_e32 v52, s8, v52
	v_lshl_add_u32 v52, v52, 2, s3
	ds_write2st64_b32 v52, v51, v206 offset1:16

.LBB0_2174:
	v_cmp_ge_u32_e32 vcc, v49, v223
	s_and_saveexec_b64 s[6:7], vcc
	s_cbranch_execz .LBB0_2176
	v_mbcnt_lo_u32_b32 v51, vcc_lo, 0
	v_mbcnt_hi_u32_b32 v50, vcc_hi, v51
	v_add_u32_e32 v50, s8, v50
	v_lshl_add_u32 v50, v50, 2, s3
	ds_write2st64_b32 v50, v49, v208 offset1:16

.LBB0_2178:
	v_cmp_ge_u32_e32 vcc, v47, v223
	s_and_saveexec_b64 s[6:7], vcc
	s_cbranch_execz .LBB0_2180
	v_mbcnt_lo_u32_b32 v49, vcc_lo, 0
	v_mbcnt_hi_u32_b32 v48, vcc_hi, v49
	v_add_u32_e32 v48, s8, v48
	v_lshl_add_u32 v48, v48, 2, s3
	v_or_b32_e32 v49, 0x440, v186
	ds_write2st64_b32 v48, v47, v49 offset1:16

.LBB0_2182:
	v_cmp_ge_u32_e32 vcc, v45, v223
	s_and_saveexec_b64 s[6:7], vcc
	s_cbranch_execz .LBB0_2184
	v_mbcnt_lo_u32_b32 v47, vcc_lo, 0
	v_mbcnt_hi_u32_b32 v46, vcc_hi, v47
	v_add_u32_e32 v46, s8, v46
	v_lshl_add_u32 v46, v46, 2, s3
	v_or_b32_e32 v47, 0x4c0, v186
	ds_write2st64_b32 v46, v45, v47 offset1:16

.LBB0_2186:
	v_cmp_ge_u32_e32 vcc, v43, v223
	s_and_saveexec_b64 s[6:7], vcc
	s_cbranch_execz .LBB0_2188
	v_mbcnt_lo_u32_b32 v45, vcc_lo, 0
	v_mbcnt_hi_u32_b32 v44, vcc_hi, v45
	v_add_u32_e32 v44, s8, v44
	v_lshl_add_u32 v44, v44, 2, s3
	v_or_b32_e32 v45, 0x540, v186
	ds_write2st64_b32 v44, v43, v45 offset1:16

.LBB0_2190:
	v_cmp_ge_u32_e32 vcc, v41, v223
	s_and_saveexec_b64 s[6:7], vcc
	s_cbranch_execz .LBB0_2192
	v_mbcnt_lo_u32_b32 v43, vcc_lo, 0
	v_mbcnt_hi_u32_b32 v42, vcc_hi, v43
	v_add_u32_e32 v42, s8, v42
	v_lshl_add_u32 v42, v42, 2, s3
	v_or_b32_e32 v43, 0x5c0, v186
	ds_write2st64_b32 v42, v41, v43 offset1:16

.LBB0_2194:
	v_cmp_ge_u32_e32 vcc, v39, v223
	s_and_saveexec_b64 s[6:7], vcc
	s_cbranch_execz .LBB0_2196
	v_mbcnt_lo_u32_b32 v41, vcc_lo, 0
	v_mbcnt_hi_u32_b32 v40, vcc_hi, v41
	v_add_u32_e32 v40, s8, v40
	v_lshl_add_u32 v40, v40, 2, s3
	v_or_b32_e32 v41, 0x640, v186
	ds_write2st64_b32 v40, v39, v41 offset1:16

.LBB0_2198:
	v_cmp_ge_u32_e32 vcc, v37, v223
	s_and_saveexec_b64 s[6:7], vcc
	s_cbranch_execz .LBB0_2200
	v_mbcnt_lo_u32_b32 v39, vcc_lo, 0
	v_mbcnt_hi_u32_b32 v38, vcc_hi, v39
	v_add_u32_e32 v38, s8, v38
	v_lshl_add_u32 v38, v38, 2, s3
	v_or_b32_e32 v39, 0x6c0, v186
	ds_write2st64_b32 v38, v37, v39 offset1:16

.LBB0_2202:
	v_cmp_ge_u32_e32 vcc, v35, v223
	s_and_saveexec_b64 s[6:7], vcc
	s_cbranch_execz .LBB0_2204
	v_mbcnt_lo_u32_b32 v37, vcc_lo, 0
	v_mbcnt_hi_u32_b32 v36, vcc_hi, v37
	v_add_u32_e32 v36, s8, v36
	v_lshl_add_u32 v36, v36, 2, s3
	v_or_b32_e32 v37, 0x740, v186
	ds_write2st64_b32 v36, v35, v37 offset1:16

.LBB0_2206:
	v_cmp_ge_u32_e32 vcc, v33, v223
	s_and_saveexec_b64 s[6:7], vcc
	s_cbranch_execz .LBB0_2208
	v_mbcnt_lo_u32_b32 v35, vcc_lo, 0
	v_mbcnt_hi_u32_b32 v34, vcc_hi, v35
	v_add_u32_e32 v34, s8, v34
	v_lshl_add_u32 v34, v34, 2, s3
	ds_write2st64_b32 v34, v33, v225 offset1:16

.LBB0_2210:
	v_cmp_ge_u32_e32 vcc, v31, v223
	s_and_saveexec_b64 s[6:7], vcc
	s_cbranch_execz .LBB0_2212
	v_mbcnt_lo_u32_b32 v33, vcc_lo, 0
	v_mbcnt_hi_u32_b32 v32, vcc_hi, v33
	v_add_u32_e32 v32, s8, v32
	v_lshl_add_u32 v32, v32, 2, s3
	v_or_b32_e32 v33, 0x840, v186
	ds_write2st64_b32 v32, v31, v33 offset1:16

.LBB0_2214:
	v_cmp_ge_u32_e32 vcc, v29, v223
	s_and_saveexec_b64 s[6:7], vcc
	s_cbranch_execz .LBB0_2216
	v_mbcnt_lo_u32_b32 v31, vcc_lo, 0
	v_mbcnt_hi_u32_b32 v30, vcc_hi, v31
	v_add_u32_e32 v30, s8, v30
	v_lshl_add_u32 v30, v30, 2, s3
	v_or_b32_e32 v31, 0x8c0, v186
	ds_write2st64_b32 v30, v29, v31 offset1:16

.LBB0_2218:
	v_cmp_ge_u32_e32 vcc, v27, v223
	s_and_saveexec_b64 s[6:7], vcc
	s_cbranch_execz .LBB0_2220
	v_mbcnt_lo_u32_b32 v29, vcc_lo, 0
	v_mbcnt_hi_u32_b32 v28, vcc_hi, v29
	v_add_u32_e32 v28, s8, v28
	v_lshl_add_u32 v28, v28, 2, s3
	v_or_b32_e32 v29, 0x940, v186
	ds_write2st64_b32 v28, v27, v29 offset1:16

.LBB0_2222:
	v_cmp_ge_u32_e32 vcc, v25, v223
	s_and_saveexec_b64 s[6:7], vcc
	s_cbranch_execz .LBB0_2224
	v_mbcnt_lo_u32_b32 v27, vcc_lo, 0
	v_mbcnt_hi_u32_b32 v26, vcc_hi, v27
	v_add_u32_e32 v26, s8, v26
	v_lshl_add_u32 v26, v26, 2, s3
	v_or_b32_e32 v27, 0x9c0, v186
	ds_write2st64_b32 v26, v25, v27 offset1:16

.LBB0_2226:
	v_cmp_ge_u32_e32 vcc, v23, v223
	s_and_saveexec_b64 s[6:7], vcc
	s_cbranch_execz .LBB0_2228
	v_mbcnt_lo_u32_b32 v25, vcc_lo, 0
	v_mbcnt_hi_u32_b32 v24, vcc_hi, v25
	v_add_u32_e32 v24, s8, v24
	v_lshl_add_u32 v24, v24, 2, s3
	v_or_b32_e32 v25, 0xa40, v186
	ds_write2st64_b32 v24, v23, v25 offset1:16

.LBB0_2230:
	v_cmp_ge_u32_e32 vcc, v21, v223
	s_and_saveexec_b64 s[6:7], vcc
	s_cbranch_execz .LBB0_2232
	v_mbcnt_lo_u32_b32 v23, vcc_lo, 0
	v_mbcnt_hi_u32_b32 v22, vcc_hi, v23
	v_add_u32_e32 v22, s8, v22
	v_lshl_add_u32 v22, v22, 2, s3
	v_or_b32_e32 v23, 0xac0, v186
	ds_write2st64_b32 v22, v21, v23 offset1:16

.LBB0_2234:
	v_cmp_ge_u32_e32 vcc, v19, v223
	s_and_saveexec_b64 s[6:7], vcc
	s_cbranch_execz .LBB0_2236
	v_mbcnt_lo_u32_b32 v21, vcc_lo, 0
	v_mbcnt_hi_u32_b32 v20, vcc_hi, v21
	v_add_u32_e32 v20, s8, v20
	v_lshl_add_u32 v20, v20, 2, s3
	v_or_b32_e32 v21, 0xb40, v186
	ds_write2st64_b32 v20, v19, v21 offset1:16

.LBB0_2238:
	v_cmp_ge_u32_e32 vcc, v17, v223
	s_and_saveexec_b64 s[6:7], vcc
	s_cbranch_execz .LBB0_2240
	v_mbcnt_lo_u32_b32 v19, vcc_lo, 0
	v_mbcnt_hi_u32_b32 v18, vcc_hi, v19
	v_add_u32_e32 v18, s8, v18
	v_lshl_add_u32 v18, v18, 2, s3
	ds_write2st64_b32 v18, v17, v241 offset1:16

.LBB0_2242:
	v_cmp_ge_u32_e32 vcc, v15, v223
	s_and_saveexec_b64 s[6:7], vcc
	s_cbranch_execz .LBB0_2244
	v_mbcnt_lo_u32_b32 v17, vcc_lo, 0
	v_mbcnt_hi_u32_b32 v16, vcc_hi, v17
	v_add_u32_e32 v16, s8, v16
	v_lshl_add_u32 v16, v16, 2, s3
	v_or_b32_e32 v17, 0xc40, v186
	ds_write2st64_b32 v16, v15, v17 offset1:16

.LBB0_2246:
	v_cmp_ge_u32_e32 vcc, v13, v223
	s_and_saveexec_b64 s[6:7], vcc
	s_cbranch_execz .LBB0_2248
	v_mbcnt_lo_u32_b32 v15, vcc_lo, 0
	v_mbcnt_hi_u32_b32 v14, vcc_hi, v15
	v_add_u32_e32 v14, s8, v14
	v_lshl_add_u32 v14, v14, 2, s3
	v_or_b32_e32 v15, 0xcc0, v186
	ds_write2st64_b32 v14, v13, v15 offset1:16

.LBB0_2250:
	v_cmp_ge_u32_e32 vcc, v11, v223
	s_and_saveexec_b64 s[6:7], vcc
	s_cbranch_execz .LBB0_2252
	v_mbcnt_lo_u32_b32 v13, vcc_lo, 0
	v_mbcnt_hi_u32_b32 v12, vcc_hi, v13
	v_add_u32_e32 v12, s8, v12
	v_lshl_add_u32 v12, v12, 2, s3
	ds_write2st64_b32 v12, v11, v247 offset1:16

.LBB0_2254:
	v_cmp_ge_u32_e32 vcc, v9, v223
	s_and_saveexec_b64 s[6:7], vcc
	s_cbranch_execz .LBB0_2256
	v_mbcnt_lo_u32_b32 v11, vcc_lo, 0
	v_mbcnt_hi_u32_b32 v10, vcc_hi, v11
	v_add_u32_e32 v10, s8, v10
	v_lshl_add_u32 v10, v10, 2, s3
	ds_write2st64_b32 v10, v9, v249 offset1:16

.LBB0_2258:
	v_cmp_ge_u32_e32 vcc, v7, v223
	s_and_saveexec_b64 s[6:7], vcc
	s_cbranch_execz .LBB0_2260
	v_mbcnt_lo_u32_b32 v9, vcc_lo, 0
	v_mbcnt_hi_u32_b32 v8, vcc_hi, v9
	v_add_u32_e32 v8, s8, v8
	v_lshl_add_u32 v8, v8, 2, s3
	ds_write2st64_b32 v8, v7, v251 offset1:16

.LBB0_2262:
	v_cmp_ge_u32_e32 vcc, v5, v223
	s_and_saveexec_b64 s[6:7], vcc
	s_cbranch_execz .LBB0_2264
	v_mbcnt_lo_u32_b32 v7, vcc_lo, 0
	v_mbcnt_hi_u32_b32 v6, vcc_hi, v7
	v_add_u32_e32 v6, s8, v6
	v_lshl_add_u32 v6, v6, 2, s3
	ds_write2st64_b32 v6, v5, v253 offset1:16

.LBB0_2266:
	v_cmp_ge_u32_e32 vcc, v3, v223
	s_and_saveexec_b64 s[6:7], vcc
	s_cbranch_execz .LBB0_2268
	v_mbcnt_lo_u32_b32 v5, vcc_lo, 0
	v_mbcnt_hi_u32_b32 v4, vcc_hi, v5
	v_add_u32_e32 v4, s8, v4
	v_lshl_add_u32 v4, v4, 2, s3
	ds_write2st64_b32 v4, v3, v255 offset1:16

.LBB0_2272:
	v_cmp_ge_u32_e32 vcc, v62, v223
	s_and_saveexec_b64 s[6:7], vcc
	s_cbranch_execz .LBB0_2274
	v_mbcnt_lo_u32_b32 v64, vcc_lo, 0
	v_mbcnt_hi_u32_b32 v63, vcc_hi, v64
	v_add_u32_e32 v63, s8, v63
	v_lshl_add_u32 v63, v63, 2, s3
	ds_write2st64_b32 v63, v62, v195 offset1:16

.LBB0_2276:
	v_cmp_ge_u32_e32 vcc, v60, v223
	s_and_saveexec_b64 s[6:7], vcc
	s_cbranch_execz .LBB0_2278
	v_mbcnt_lo_u32_b32 v62, vcc_lo, 0
	v_mbcnt_hi_u32_b32 v61, vcc_hi, v62
	v_add_u32_e32 v61, s8, v61
	v_lshl_add_u32 v61, v61, 2, s3
	ds_write2st64_b32 v61, v60, v197 offset1:16

.LBB0_2280:
	v_cmp_ge_u32_e32 vcc, v58, v223
	s_and_saveexec_b64 s[6:7], vcc
	s_cbranch_execz .LBB0_2282
	v_mbcnt_lo_u32_b32 v60, vcc_lo, 0
	v_mbcnt_hi_u32_b32 v59, vcc_hi, v60
	v_add_u32_e32 v59, s8, v59
	v_lshl_add_u32 v59, v59, 2, s3
	ds_write2st64_b32 v59, v58, v199 offset1:16

.LBB0_2284:
	v_cmp_ge_u32_e32 vcc, v56, v223
	s_and_saveexec_b64 s[6:7], vcc
	s_cbranch_execz .LBB0_2286
	v_mbcnt_lo_u32_b32 v58, vcc_lo, 0
	v_mbcnt_hi_u32_b32 v57, vcc_hi, v58
	v_add_u32_e32 v57, s8, v57
	v_lshl_add_u32 v57, v57, 2, s3
	ds_write2st64_b32 v57, v56, v201 offset1:16

.LBB0_2288:
	v_cmp_ge_u32_e32 vcc, v54, v223
	s_and_saveexec_b64 s[6:7], vcc
	s_cbranch_execz .LBB0_2290
	v_mbcnt_lo_u32_b32 v56, vcc_lo, 0
	v_mbcnt_hi_u32_b32 v55, vcc_hi, v56
	v_add_u32_e32 v55, s8, v55
	v_lshl_add_u32 v55, v55, 2, s3
	ds_write2st64_b32 v55, v54, v203 offset1:16

.LBB0_2292:
	v_cmp_ge_u32_e32 vcc, v52, v223
	s_and_saveexec_b64 s[6:7], vcc
	s_cbranch_execz .LBB0_2294
	v_mbcnt_lo_u32_b32 v54, vcc_lo, 0
	v_mbcnt_hi_u32_b32 v53, vcc_hi, v54
	v_add_u32_e32 v53, s8, v53
	v_lshl_add_u32 v53, v53, 2, s3
	ds_write2st64_b32 v53, v52, v205 offset1:16

.LBB0_2296:
	v_cmp_ge_u32_e32 vcc, v50, v223
	s_and_saveexec_b64 s[6:7], vcc
	s_cbranch_execz .LBB0_2298
	v_mbcnt_lo_u32_b32 v52, vcc_lo, 0
	v_mbcnt_hi_u32_b32 v51, vcc_hi, v52
	v_add_u32_e32 v51, s8, v51
	v_lshl_add_u32 v51, v51, 2, s3
	ds_write2st64_b32 v51, v50, v207 offset1:16

.LBB0_2300:
	v_cmp_ge_u32_e32 vcc, v48, v223
	s_and_saveexec_b64 s[6:7], vcc
	s_cbranch_execz .LBB0_2302
	v_mbcnt_lo_u32_b32 v50, vcc_lo, 0
	v_mbcnt_hi_u32_b32 v49, vcc_hi, v50
	v_add_u32_e32 v49, s8, v49
	v_lshl_add_u32 v49, v49, 2, s3
	v_or_b32_e32 v50, 0x400, v186
	ds_write2st64_b32 v49, v48, v50 offset1:16

.LBB0_2304:
	v_cmp_ge_u32_e32 vcc, v46, v223
	s_and_saveexec_b64 s[6:7], vcc
	s_cbranch_execz .LBB0_2306
	v_mbcnt_lo_u32_b32 v48, vcc_lo, 0
	v_mbcnt_hi_u32_b32 v47, vcc_hi, v48
	v_add_u32_e32 v47, s8, v47
	v_lshl_add_u32 v47, v47, 2, s3
	v_or_b32_e32 v48, 0x480, v186
	ds_write2st64_b32 v47, v46, v48 offset1:16

.LBB0_2308:
	v_cmp_ge_u32_e32 vcc, v44, v223
	s_and_saveexec_b64 s[6:7], vcc
	s_cbranch_execz .LBB0_2310
	v_mbcnt_lo_u32_b32 v46, vcc_lo, 0
	v_mbcnt_hi_u32_b32 v45, vcc_hi, v46
	v_add_u32_e32 v45, s8, v45
	v_lshl_add_u32 v45, v45, 2, s3
	v_or_b32_e32 v46, 0x500, v186
	ds_write2st64_b32 v45, v44, v46 offset1:16

.LBB0_2312:
	v_cmp_ge_u32_e32 vcc, v42, v223
	s_and_saveexec_b64 s[6:7], vcc
	s_cbranch_execz .LBB0_2314
	v_mbcnt_lo_u32_b32 v44, vcc_lo, 0
	v_mbcnt_hi_u32_b32 v43, vcc_hi, v44
	v_add_u32_e32 v43, s8, v43
	v_lshl_add_u32 v43, v43, 2, s3
	v_or_b32_e32 v44, 0x580, v186
	ds_write2st64_b32 v43, v42, v44 offset1:16

.LBB0_2316:
	v_cmp_ge_u32_e32 vcc, v40, v223
	s_and_saveexec_b64 s[6:7], vcc
	s_cbranch_execz .LBB0_2318
	v_mbcnt_lo_u32_b32 v42, vcc_lo, 0
	v_mbcnt_hi_u32_b32 v41, vcc_hi, v42
	v_add_u32_e32 v41, s8, v41
	v_lshl_add_u32 v41, v41, 2, s3
	v_or_b32_e32 v42, 0x600, v186
	ds_write2st64_b32 v41, v40, v42 offset1:16

.LBB0_2320:
	v_cmp_ge_u32_e32 vcc, v38, v223
	s_and_saveexec_b64 s[6:7], vcc
	s_cbranch_execz .LBB0_2322
	v_mbcnt_lo_u32_b32 v40, vcc_lo, 0
	v_mbcnt_hi_u32_b32 v39, vcc_hi, v40
	v_add_u32_e32 v39, s8, v39
	v_lshl_add_u32 v39, v39, 2, s3
	v_or_b32_e32 v40, 0x680, v186
	ds_write2st64_b32 v39, v38, v40 offset1:16

.LBB0_2324:
	v_cmp_ge_u32_e32 vcc, v36, v223
	s_and_saveexec_b64 s[6:7], vcc
	s_cbranch_execz .LBB0_2326
	v_mbcnt_lo_u32_b32 v38, vcc_lo, 0
	v_mbcnt_hi_u32_b32 v37, vcc_hi, v38
	v_add_u32_e32 v37, s8, v37
	v_lshl_add_u32 v37, v37, 2, s3
	v_or_b32_e32 v38, 0x700, v186
	ds_write2st64_b32 v37, v36, v38 offset1:16

.LBB0_2328:
	v_cmp_ge_u32_e32 vcc, v34, v223
	s_and_saveexec_b64 s[6:7], vcc
	s_cbranch_execz .LBB0_2330
	v_mbcnt_lo_u32_b32 v36, vcc_lo, 0
	v_mbcnt_hi_u32_b32 v35, vcc_hi, v36
	v_add_u32_e32 v35, s8, v35
	v_lshl_add_u32 v35, v35, 2, s3
	v_or_b32_e32 v36, 0x780, v186
	ds_write2st64_b32 v35, v34, v36 offset1:16

.LBB0_2332:
	v_cmp_ge_u32_e32 vcc, v32, v223
	s_and_saveexec_b64 s[6:7], vcc
	s_cbranch_execz .LBB0_2334
	v_mbcnt_lo_u32_b32 v34, vcc_lo, 0
	v_mbcnt_hi_u32_b32 v33, vcc_hi, v34
	v_add_u32_e32 v33, s8, v33
	v_lshl_add_u32 v33, v33, 2, s3
	v_or_b32_e32 v34, 0x800, v186
	ds_write2st64_b32 v33, v32, v34 offset1:16

.LBB0_2336:
	v_cmp_ge_u32_e32 vcc, v30, v223
	s_and_saveexec_b64 s[6:7], vcc
	s_cbranch_execz .LBB0_2338
	v_mbcnt_lo_u32_b32 v32, vcc_lo, 0
	v_mbcnt_hi_u32_b32 v31, vcc_hi, v32
	v_add_u32_e32 v31, s8, v31
	v_lshl_add_u32 v31, v31, 2, s3
	v_or_b32_e32 v32, 0x880, v186
	ds_write2st64_b32 v31, v30, v32 offset1:16

.LBB0_2340:
	v_cmp_ge_u32_e32 vcc, v28, v223
	s_and_saveexec_b64 s[6:7], vcc
	s_cbranch_execz .LBB0_2342
	v_mbcnt_lo_u32_b32 v30, vcc_lo, 0
	v_mbcnt_hi_u32_b32 v29, vcc_hi, v30
	v_add_u32_e32 v29, s8, v29
	v_lshl_add_u32 v29, v29, 2, s3
	v_or_b32_e32 v30, 0x900, v186
	ds_write2st64_b32 v29, v28, v30 offset1:16

.LBB0_2344:
	v_cmp_ge_u32_e32 vcc, v26, v223
	s_and_saveexec_b64 s[6:7], vcc
	s_cbranch_execz .LBB0_2346
	v_mbcnt_lo_u32_b32 v28, vcc_lo, 0
	v_mbcnt_hi_u32_b32 v27, vcc_hi, v28
	v_add_u32_e32 v27, s8, v27
	v_lshl_add_u32 v27, v27, 2, s3
	v_or_b32_e32 v28, 0x980, v186
	ds_write2st64_b32 v27, v26, v28 offset1:16

.LBB0_2348:
	v_cmp_ge_u32_e32 vcc, v24, v223
	s_and_saveexec_b64 s[6:7], vcc
	s_cbranch_execz .LBB0_2350
	v_mbcnt_lo_u32_b32 v26, vcc_lo, 0
	v_mbcnt_hi_u32_b32 v25, vcc_hi, v26
	v_add_u32_e32 v25, s8, v25
	v_lshl_add_u32 v25, v25, 2, s3
	v_or_b32_e32 v26, 0xa00, v186
	ds_write2st64_b32 v25, v24, v26 offset1:16

.LBB0_2352:
	v_cmp_ge_u32_e32 vcc, v22, v223
	s_and_saveexec_b64 s[6:7], vcc
	s_cbranch_execz .LBB0_2354
	v_mbcnt_lo_u32_b32 v24, vcc_lo, 0
	v_mbcnt_hi_u32_b32 v23, vcc_hi, v24
	v_add_u32_e32 v23, s8, v23
	v_lshl_add_u32 v23, v23, 2, s3
	v_or_b32_e32 v24, 0xa80, v186
	ds_write2st64_b32 v23, v22, v24 offset1:16

.LBB0_2356:
	v_cmp_ge_u32_e32 vcc, v20, v223
	s_and_saveexec_b64 s[6:7], vcc
	s_cbranch_execz .LBB0_2358
	v_mbcnt_lo_u32_b32 v22, vcc_lo, 0
	v_mbcnt_hi_u32_b32 v21, vcc_hi, v22
	v_add_u32_e32 v21, s8, v21
	v_lshl_add_u32 v21, v21, 2, s3
	v_or_b32_e32 v22, 0xb00, v186
	ds_write2st64_b32 v21, v20, v22 offset1:16

.LBB0_2360:
	v_cmp_ge_u32_e32 vcc, v18, v223
	s_and_saveexec_b64 s[6:7], vcc
	s_cbranch_execz .LBB0_2362
	v_mbcnt_lo_u32_b32 v20, vcc_lo, 0
	v_mbcnt_hi_u32_b32 v19, vcc_hi, v20
	v_add_u32_e32 v19, s8, v19
	v_lshl_add_u32 v19, v19, 2, s3
	v_or_b32_e32 v20, 0xb80, v186
	ds_write2st64_b32 v19, v18, v20 offset1:16

.LBB0_2364:
	v_cmp_ge_u32_e32 vcc, v16, v223
	s_and_saveexec_b64 s[6:7], vcc
	s_cbranch_execz .LBB0_2366
	v_mbcnt_lo_u32_b32 v18, vcc_lo, 0
	v_mbcnt_hi_u32_b32 v17, vcc_hi, v18
	v_add_u32_e32 v17, s8, v17
	v_lshl_add_u32 v17, v17, 2, s3
	v_or_b32_e32 v18, 0xc00, v186
	ds_write2st64_b32 v17, v16, v18 offset1:16

.LBB0_2368:
	v_cmp_ge_u32_e32 vcc, v14, v223
	s_and_saveexec_b64 s[6:7], vcc
	s_cbranch_execz .LBB0_2370
	v_mbcnt_lo_u32_b32 v16, vcc_lo, 0
	v_mbcnt_hi_u32_b32 v15, vcc_hi, v16
	v_add_u32_e32 v15, s8, v15
	v_lshl_add_u32 v15, v15, 2, s3
	ds_write2st64_b32 v15, v14, v240 offset1:16

.LBB0_2372:
	v_cmp_ge_u32_e32 vcc, v12, v223
	s_and_saveexec_b64 s[6:7], vcc
	s_cbranch_execz .LBB0_2374
	v_mbcnt_lo_u32_b32 v14, vcc_lo, 0
	v_mbcnt_hi_u32_b32 v13, vcc_hi, v14
	v_add_u32_e32 v13, s8, v13
	v_lshl_add_u32 v13, v13, 2, s3
	ds_write2st64_b32 v13, v12, v246 offset1:16

.LBB0_2376:
	v_cmp_ge_u32_e32 vcc, v10, v223
	s_and_saveexec_b64 s[6:7], vcc
	s_cbranch_execz .LBB0_2378
	v_mbcnt_lo_u32_b32 v12, vcc_lo, 0
	v_mbcnt_hi_u32_b32 v11, vcc_hi, v12
	v_add_u32_e32 v11, s8, v11
	v_lshl_add_u32 v11, v11, 2, s3
	ds_write2st64_b32 v11, v10, v248 offset1:16

.LBB0_2380:
	v_cmp_ge_u32_e32 vcc, v8, v223
	s_and_saveexec_b64 s[6:7], vcc
	s_cbranch_execz .LBB0_2382
	v_mbcnt_lo_u32_b32 v10, vcc_lo, 0
	v_mbcnt_hi_u32_b32 v9, vcc_hi, v10
	v_add_u32_e32 v9, s8, v9
	v_lshl_add_u32 v9, v9, 2, s3
	ds_write2st64_b32 v9, v8, v250 offset1:16

.LBB0_2384:
	v_cmp_ge_u32_e32 vcc, v6, v223
	s_and_saveexec_b64 s[6:7], vcc
	s_cbranch_execz .LBB0_2386
	v_mbcnt_lo_u32_b32 v8, vcc_lo, 0
	v_mbcnt_hi_u32_b32 v7, vcc_hi, v8
	v_add_u32_e32 v7, s8, v7
	v_lshl_add_u32 v7, v7, 2, s3
	ds_write2st64_b32 v7, v6, v252 offset1:16

.LBB0_2388:
	v_cmp_ge_u32_e32 vcc, v4, v223
	s_and_saveexec_b64 s[6:7], vcc
	s_cbranch_execz .LBB0_2390
	v_mbcnt_lo_u32_b32 v6, vcc_lo, 0
	v_mbcnt_hi_u32_b32 v5, vcc_hi, v6
	v_add_u32_e32 v5, s8, v5
	v_lshl_add_u32 v5, v5, 2, s3
	ds_write2st64_b32 v5, v4, v254 offset1:16

.LBB0_2392:
	v_cmp_ge_u32_e32 vcc, v2, v223
	s_and_saveexec_b64 s[6:7], vcc
	s_cbranch_execz .LBB0_2394
	v_mbcnt_lo_u32_b32 v4, vcc_lo, 0
	v_mbcnt_hi_u32_b32 v3, vcc_hi, v4
	v_add_u32_e32 v3, s8, v3
	v_lshl_add_u32 v3, v3, 2, s3
	ds_write2st64_b32 v3, v2, v210 offset1:16

.LBB0_2395:
	v_cmp_ge_u32_e32 vcc, v0, v223
	s_and_saveexec_b64 s[6:7], vcc
	s_cbranch_execz .LBB0_2397
	v_mbcnt_lo_u32_b32 v3, vcc_lo, 0
	v_mbcnt_hi_u32_b32 v2, vcc_hi, v3
	v_add_u32_e32 v2, s8, v2
	v_lshl_add_u32 v2, v2, 2, s3
	ds_write2st64_b32 v2, v0, v211 offset1:16

.LBB0_2452:
	s_sub_i32 s58, 0x100, s12
	s_cmp_lt_i32 s57, 1
	s_cbranch_scc1 .LBB0_2598
	v_cmp_eq_u32_e32 vcc, v17, v0
	s_and_b64 s[10:11], s[10:11], vcc
	v_cndmask_b32_e64 v18, 0, 1, s[10:11]
	v_cmp_ne_u32_e32 vcc, 0, v18
	s_nop 1
	v_mbcnt_lo_u32_b32 v19, vcc_lo, 0
	v_mbcnt_hi_u32_b32 v18, vcc_hi, v19
	v_cmp_gt_u32_e64 s[12:13], s58, v18
	s_nop 1
	v_cndmask_b32_e64 v18, 0, 1, s[12:13]
	v_cmp_gt_u32_e64 s[12:13], v17, v0
	s_nop 1
	v_cndmask_b32_e64 v17, 0, 1, s[12:13]
	v_cndmask_b32_e64 v17, v17, v18, s[10:11]
	v_and_b32_e32 v17, 1, v17
	v_cmp_eq_u32_e64 s[12:13], 1, v17
	v_cmp_ne_u32_e64 s[10:11], 0, v17
	s_and_saveexec_b64 s[40:41], s[12:13]
	s_cbranch_execz .LBB0_2455
	ds_read_b32 v18, v190 offset:4096
	v_mbcnt_lo_u32_b32 v19, s10, 0
	v_mbcnt_hi_u32_b32 v17, s11, v19
	v_lshl_add_u32 v17, v17, 2, s43
	s_waitcnt lgkmcnt(0)
	ds_write_b32 v17, v18

.LBB0_2456:
	v_cmp_eq_u32_e32 vcc, v3, v0
	s_and_b64 s[8:9], vcc, s[8:9]
	v_cndmask_b32_e64 v17, 0, 1, s[8:9]
	v_cmp_ne_u32_e32 vcc, 0, v17
	s_nop 1
	v_mbcnt_lo_u32_b32 v18, vcc_lo, 0
	v_mbcnt_hi_u32_b32 v17, vcc_hi, v18
	v_add_u32_e32 v17, s41, v17
	v_cmp_gt_u32_e64 s[10:11], s58, v17
	s_nop 1
	v_cndmask_b32_e64 v17, 0, 1, s[10:11]
	v_cmp_gt_u32_e64 s[10:11], v3, v0
	s_nop 1
	v_cndmask_b32_e64 v3, 0, 1, s[10:11]
	v_cndmask_b32_e64 v3, v3, v17, s[8:9]
	v_and_b32_e32 v3, 1, v3
	v_cmp_eq_u32_e64 s[10:11], 1, v3
	v_cmp_ne_u32_e64 s[8:9], 0, v3
	s_and_saveexec_b64 s[12:13], s[10:11]
	s_cbranch_execz .LBB0_2458
	ds_read_b32 v17, v190 offset:4352
	v_and_b32_e32 v18, s8, v168
	s_lshl_b32 s10, s40, 2
	v_and_b32_e32 v3, s9, v169
	v_bcnt_u32_b32 v18, v18, 0
	s_add_i32 s10, s43, s10
	v_bcnt_u32_b32 v3, v3, v18
	v_lshl_add_u32 v3, v3, 2, s10
	s_waitcnt lgkmcnt(0)
	ds_write_b32 v3, v17

.LBB0_2460:
	v_cmp_eq_u32_e32 vcc, v16, v0
	v_cmp_gt_u32_e64 s[6:7], s56, v196
	s_and_b64 s[6:7], vcc, s[6:7]
	s_nop 0
	v_cndmask_b32_e64 v2, 0, 1, s[6:7]
	v_cmp_ne_u32_e32 vcc, 0, v2
	s_nop 1
	v_mbcnt_lo_u32_b32 v3, vcc_lo, 0
	v_mbcnt_hi_u32_b32 v2, vcc_hi, v3
	v_add_u32_e32 v2, s41, v2
	v_cmp_gt_u32_e64 s[8:9], s58, v2
	s_nop 1
	v_cndmask_b32_e64 v2, 0, 1, s[8:9]
	v_cmp_gt_u32_e64 s[8:9], v16, v0
	s_nop 1
	v_cndmask_b32_e64 v3, 0, 1, s[8:9]
	v_cndmask_b32_e64 v2, v3, v2, s[6:7]
	v_and_b32_e32 v2, 1, v2
	v_cmp_eq_u32_e64 s[8:9], 1, v2
	v_cmp_ne_u32_e64 s[6:7], 0, v2
	s_and_saveexec_b64 s[10:11], s[8:9]
	s_cbranch_execz .LBB0_2462
	ds_read_b32 v3, v190 offset:4864
	v_and_b32_e32 v16, s6, v168
	s_lshl_b32 s8, s40, 2
	v_and_b32_e32 v2, s7, v169
	v_bcnt_u32_b32 v16, v16, 0
	s_add_i32 s8, s43, s8
	v_bcnt_u32_b32 v2, v2, v16
	v_lshl_add_u32 v2, v2, 2, s8
	s_waitcnt lgkmcnt(0)
	ds_write_b32 v2, v3

.LBB0_2464:
	v_cmp_eq_u32_e32 vcc, v14, v0
	v_cmp_gt_u32_e64 s[6:7], s56, v198
	s_and_b64 s[6:7], vcc, s[6:7]
	s_nop 0
	v_cndmask_b32_e64 v2, 0, 1, s[6:7]
	v_cmp_ne_u32_e32 vcc, 0, v2
	s_nop 1
	v_mbcnt_lo_u32_b32 v3, vcc_lo, 0
	v_mbcnt_hi_u32_b32 v2, vcc_hi, v3
	v_add_u32_e32 v2, s41, v2
	v_cmp_gt_u32_e64 s[8:9], s58, v2
	s_nop 1
	v_cndmask_b32_e64 v2, 0, 1, s[8:9]
	v_cmp_gt_u32_e64 s[8:9], v14, v0
	s_nop 1
	v_cndmask_b32_e64 v3, 0, 1, s[8:9]
	v_cndmask_b32_e64 v2, v3, v2, s[6:7]
	v_and_b32_e32 v2, 1, v2
	v_cmp_ne_u32_e64 s[6:7], 0, v2
	v_cmp_eq_u32_e64 s[8:9], 1, v2
	s_nop 0
	v_mbcnt_lo_u32_b32 v3, s6, 0
	v_mbcnt_hi_u32_b32 v2, s7, v3
	v_add_u32_e32 v2, s40, v2
	v_cmp_gt_u32_e64 s[10:11], s48, v2
	s_and_b64 s[10:11], s[8:9], s[10:11]
	s_and_saveexec_b64 s[8:9], s[10:11]
	s_cbranch_execz .LBB0_2466
	ds_read_b32 v3, v190 offset:5376
	v_lshl_add_u32 v2, v2, 2, s43
	s_waitcnt lgkmcnt(0)
	ds_write_b32 v2, v3

.LBB0_2468:
	v_cmp_eq_u32_e32 vcc, v12, v0
	v_cmp_gt_u32_e64 s[6:7], s56, v200
	s_and_b64 s[6:7], vcc, s[6:7]
	s_nop 0
	v_cndmask_b32_e64 v2, 0, 1, s[6:7]
	v_cmp_ne_u32_e32 vcc, 0, v2
	s_nop 1
	v_mbcnt_lo_u32_b32 v3, vcc_lo, 0
	v_mbcnt_hi_u32_b32 v2, vcc_hi, v3
	v_add_u32_e32 v2, s41, v2
	v_cmp_gt_u32_e64 s[8:9], s58, v2
	s_nop 1
	v_cndmask_b32_e64 v2, 0, 1, s[8:9]
	v_cmp_gt_u32_e64 s[8:9], v12, v0
	s_nop 1
	v_cndmask_b32_e64 v3, 0, 1, s[8:9]
	v_cndmask_b32_e64 v2, v3, v2, s[6:7]
	v_and_b32_e32 v2, 1, v2
	v_cmp_ne_u32_e64 s[6:7], 0, v2
	v_cmp_eq_u32_e64 s[8:9], 1, v2
	s_nop 0
	v_mbcnt_lo_u32_b32 v3, s6, 0
	v_mbcnt_hi_u32_b32 v2, s7, v3
	v_add_u32_e32 v2, s40, v2
	v_cmp_gt_u32_e64 s[10:11], s48, v2
	s_and_b64 s[10:11], s[8:9], s[10:11]
	s_and_saveexec_b64 s[8:9], s[10:11]
	s_cbranch_execz .LBB0_2470
	ds_read_b32 v3, v190 offset:5888
	v_lshl_add_u32 v2, v2, 2, s43
	s_waitcnt lgkmcnt(0)
	ds_write_b32 v2, v3

.LBB0_2472:
	v_cmp_eq_u32_e32 vcc, v10, v0
	v_cmp_gt_u32_e64 s[6:7], s56, v202
	s_and_b64 s[6:7], vcc, s[6:7]
	s_nop 0
	v_cndmask_b32_e64 v2, 0, 1, s[6:7]
	v_cmp_ne_u32_e32 vcc, 0, v2
	s_nop 1
	v_mbcnt_lo_u32_b32 v3, vcc_lo, 0
	v_mbcnt_hi_u32_b32 v2, vcc_hi, v3
	v_add_u32_e32 v2, s41, v2
	v_cmp_gt_u32_e64 s[8:9], s58, v2
	s_nop 1
	v_cndmask_b32_e64 v2, 0, 1, s[8:9]
	v_cmp_gt_u32_e64 s[8:9], v10, v0
	s_nop 1
	v_cndmask_b32_e64 v3, 0, 1, s[8:9]
	v_cndmask_b32_e64 v2, v3, v2, s[6:7]
	v_and_b32_e32 v2, 1, v2
	v_cmp_ne_u32_e64 s[6:7], 0, v2
	v_cmp_eq_u32_e64 s[8:9], 1, v2
	s_nop 0
	v_mbcnt_lo_u32_b32 v3, s6, 0
	v_mbcnt_hi_u32_b32 v2, s7, v3
	v_add_u32_e32 v2, s40, v2
	v_cmp_gt_u32_e64 s[10:11], s48, v2
	s_and_b64 s[10:11], s[8:9], s[10:11]
	s_and_saveexec_b64 s[8:9], s[10:11]
	s_cbranch_execz .LBB0_2474
	ds_read_b32 v3, v190 offset:6400
	v_lshl_add_u32 v2, v2, 2, s43
	s_waitcnt lgkmcnt(0)
	ds_write_b32 v2, v3

.LBB0_2476:
	v_cmp_eq_u32_e32 vcc, v8, v0
	v_cmp_gt_u32_e64 s[6:7], s56, v204
	s_and_b64 s[6:7], vcc, s[6:7]
	s_nop 0
	v_cndmask_b32_e64 v2, 0, 1, s[6:7]
	v_cmp_ne_u32_e32 vcc, 0, v2
	s_nop 1
	v_mbcnt_lo_u32_b32 v3, vcc_lo, 0
	v_mbcnt_hi_u32_b32 v2, vcc_hi, v3
	v_add_u32_e32 v2, s41, v2
	v_cmp_gt_u32_e64 s[8:9], s58, v2
	s_nop 1
	v_cndmask_b32_e64 v2, 0, 1, s[8:9]
	v_cmp_gt_u32_e64 s[8:9], v8, v0
	s_nop 1
	v_cndmask_b32_e64 v3, 0, 1, s[8:9]
	v_cndmask_b32_e64 v2, v3, v2, s[6:7]
	v_and_b32_e32 v2, 1, v2
	v_cmp_ne_u32_e64 s[6:7], 0, v2
	v_cmp_eq_u32_e64 s[8:9], 1, v2
	s_nop 0
	v_mbcnt_lo_u32_b32 v3, s6, 0
	v_mbcnt_hi_u32_b32 v2, s7, v3
	v_add_u32_e32 v2, s40, v2
	v_cmp_gt_u32_e64 s[10:11], s48, v2
	s_and_b64 s[10:11], s[8:9], s[10:11]
	s_and_saveexec_b64 s[8:9], s[10:11]
	s_cbranch_execz .LBB0_2478
	ds_read_b32 v3, v190 offset:6912
	v_lshl_add_u32 v2, v2, 2, s43
	s_waitcnt lgkmcnt(0)
	ds_write_b32 v2, v3

.LBB0_2480:
	v_cmp_eq_u32_e32 vcc, v6, v0
	v_cmp_gt_u32_e64 s[6:7], s56, v206
	s_and_b64 s[6:7], vcc, s[6:7]
	s_nop 0
	v_cndmask_b32_e64 v2, 0, 1, s[6:7]
	v_cmp_ne_u32_e32 vcc, 0, v2
	s_nop 1
	v_mbcnt_lo_u32_b32 v3, vcc_lo, 0
	v_mbcnt_hi_u32_b32 v2, vcc_hi, v3
	v_add_u32_e32 v2, s41, v2
	v_cmp_gt_u32_e64 s[8:9], s58, v2
	s_nop 1
	v_cndmask_b32_e64 v2, 0, 1, s[8:9]
	v_cmp_gt_u32_e64 s[8:9], v6, v0
	s_nop 1
	v_cndmask_b32_e64 v3, 0, 1, s[8:9]
	v_cndmask_b32_e64 v2, v3, v2, s[6:7]
	v_and_b32_e32 v2, 1, v2
	v_cmp_ne_u32_e64 s[6:7], 0, v2
	v_cmp_eq_u32_e64 s[8:9], 1, v2
	s_nop 0
	v_mbcnt_lo_u32_b32 v3, s6, 0
	v_mbcnt_hi_u32_b32 v2, s7, v3
	v_add_u32_e32 v2, s40, v2
	v_cmp_gt_u32_e64 s[10:11], s48, v2
	s_and_b64 s[10:11], s[8:9], s[10:11]
	s_and_saveexec_b64 s[8:9], s[10:11]
	s_cbranch_execz .LBB0_2482
	ds_read_b32 v3, v190 offset:7424
	v_lshl_add_u32 v2, v2, 2, s43
	s_waitcnt lgkmcnt(0)
	ds_write_b32 v2, v3

.LBB0_2552:
	s_or_b64 exec, exec, s[12:13]
	v_lshl_add_u32 v0, v0, 2, v191
	ds_read_b128 v[128:131], v0
	v_add_f32_e32 v0, v118, v122
	v_add_f32_e32 v3, v117, v121
	v_cndmask_b32_e32 v117, v220, v0, vcc
	v_add_f32_e32 v0, v119, v123
	v_cndmask_b32_e32 v118, v220, v0, vcc
	s_waitcnt lgkmcnt(0)
	v_add_f32_e32 v0, v124, v128
	v_cndmask_b32_e64 v119, v220, v0, s[6:7]
	v_add_f32_e32 v0, v125, v129
	v_add_f32_e32 v2, v116, v120
	v_cndmask_b32_e64 v120, v220, v0, s[6:7]
	v_add_f32_e32 v0, v126, v130
	v_cndmask_b32_e32 v2, v220, v2, vcc
	v_cndmask_b32_e64 v121, v220, v0, s[6:7]
	v_add_f32_e32 v0, v127, v131
	v_cndmask_b32_e64 v122, v220, v0, s[6:7]
	v_max_f32_e32 v0, v2, v119
	v_cndmask_b32_e32 v116, v220, v3, vcc
	s_nop 0
	v_max_f32_dpp v0, v0, v0 quad_perm:[1,0,3,2] row_mask:0xf bank_mask:0xf bound_ctrl:1
	s_nop 1
	v_max_f32_dpp v0, v0, v0 quad_perm:[2,3,0,1] row_mask:0xf bank_mask:0xf bound_ctrl:1
	s_nop 1
	v_max_f32_dpp v0, v0, v0 row_half_mirror row_mask:0xf bank_mask:0xf bound_ctrl:1
	s_nop 1
	v_mov_b32_dpp v3, v0 row_mirror row_mask:0xf bank_mask:0xf bound_ctrl:1
	v_max3_f32 v0, v233, v0, v3
	v_sub_f32_e32 v2, v2, v0
	v_sub_f32_e32 v3, v233, v0
	v_mul_f32_e32 v2, 0x3fb8aa3b, v2
	v_mul_f32_e32 v123, 0x3fb8aa3b, v3
	v_exp_f32_e32 v3, v2
	v_sub_f32_e32 v2, v119, v0
	v_mul_f32_e32 v2, 0x3fb8aa3b, v2
	v_exp_f32_e32 v159, v2
	v_cvt_pk_bf16_f32 v2, v3, s0
	ds_write_b16 v221, v2 offset:8704
	v_exp_f32_e32 v161, v123
	v_cvt_pk_bf16_f32 v2, v159, s0
	ds_write_b16 v221, v2 offset:8736
	v_max_f32_e32 v2, v116, v120
	v_cmp_neq_f32_e32 vcc, 1.0, v161
	s_nop 0
	v_max_f32_dpp v2, v2, v2 quad_perm:[1,0,3,2] row_mask:0xf bank_mask:0xf bound_ctrl:1
	s_nop 1
	v_max_f32_dpp v2, v2, v2 quad_perm:[2,3,0,1] row_mask:0xf bank_mask:0xf bound_ctrl:1
	s_nop 1
	v_max_f32_dpp v2, v2, v2 row_half_mirror row_mask:0xf bank_mask:0xf bound_ctrl:1
	s_nop 1
	v_mov_b32_dpp v119, v2 row_mirror row_mask:0xf bank_mask:0xf bound_ctrl:1
	v_max3_f32 v226, v232, v2, v119
	v_sub_f32_e32 v2, v232, v226
	v_mul_f32_e32 v119, 0x3fb8aa3b, v2
	v_sub_f32_e32 v2, v116, v226
	v_mul_f32_e32 v2, 0x3fb8aa3b, v2
	v_sub_f32_e32 v116, v120, v226
	v_exp_f32_e32 v2, v2
	v_mul_f32_e32 v116, 0x3fb8aa3b, v116
	v_exp_f32_e32 v158, v116
	v_exp_f32_e32 v160, v119
	v_cvt_pk_bf16_f32 v116, v2, s0
	ds_write_b16 v221, v116 offset:8784
	v_cvt_pk_bf16_f32 v116, v158, s0
	ds_write_b16 v221, v116 offset:8816
	v_max_f32_e32 v116, v117, v121
	v_cmp_neq_f32_e64 s[6:7], 1.0, v160
	s_or_b64 s[6:7], vcc, s[6:7]
	v_max_f32_dpp v116, v116, v116 quad_perm:[1,0,3,2] row_mask:0xf bank_mask:0xf bound_ctrl:1
	s_nop 1
	v_max_f32_dpp v116, v116, v116 quad_perm:[2,3,0,1] row_mask:0xf bank_mask:0xf bound_ctrl:1
	s_nop 1
	v_max_f32_dpp v116, v116, v116 row_half_mirror row_mask:0xf bank_mask:0xf bound_ctrl:1
	s_nop 1
	v_mov_b32_dpp v119, v116 row_mirror row_mask:0xf bank_mask:0xf bound_ctrl:1
	v_max3_f32 v227, v231, v116, v119
	v_sub_f32_e32 v117, v117, v227
	v_mul_f32_e32 v117, 0x3fb8aa3b, v117
	v_exp_f32_e32 v181, v117
	v_sub_f32_e32 v117, v121, v227
	v_mul_f32_e32 v117, 0x3fb8aa3b, v117
	v_exp_f32_e32 v183, v117
	v_sub_f32_e32 v116, v231, v227
	v_mul_f32_e32 v116, 0x3fb8aa3b, v116
	v_exp_f32_e32 v185, v116
	v_cvt_pk_bf16_f32 v116, v181, s0
	ds_write_b16 v221, v116 offset:8864
	v_cvt_pk_bf16_f32 v116, v183, s0
	ds_write_b16 v221, v116 offset:8896
	v_max_f32_e32 v116, v118, v122
	v_cmp_neq_f32_e32 vcc, 1.0, v185
	s_or_b64 s[6:7], s[6:7], vcc
	v_max_f32_dpp v116, v116, v116 quad_perm:[1,0,3,2] row_mask:0xf bank_mask:0xf bound_ctrl:1
	s_nop 1
	v_max_f32_dpp v116, v116, v116 quad_perm:[2,3,0,1] row_mask:0xf bank_mask:0xf bound_ctrl:1
	s_nop 1
	v_max_f32_dpp v116, v116, v116 row_half_mirror row_mask:0xf bank_mask:0xf bound_ctrl:1
	s_nop 1
	v_mov_b32_dpp v117, v116 row_mirror row_mask:0xf bank_mask:0xf bound_ctrl:1
	v_max3_f32 v224, v230, v116, v117
	v_sub_f32_e32 v117, v118, v224
	v_mul_f32_e32 v117, 0x3fb8aa3b, v117
	v_exp_f32_e32 v180, v117
	v_sub_f32_e32 v117, v122, v224
	v_mul_f32_e32 v117, 0x3fb8aa3b, v117
	v_exp_f32_e32 v182, v117
	v_sub_f32_e32 v116, v230, v224
	v_mul_f32_e32 v116, 0x3fb8aa3b, v116
	v_exp_f32_e32 v184, v116
	v_cvt_pk_bf16_f32 v116, v180, s0
	ds_write_b16 v221, v116 offset:8944
	v_cvt_pk_bf16_f32 v116, v182, s0
	ds_write_b16 v221, v116 offset:8976
	s_waitcnt lgkmcnt(0)
	ds_read_b128 v[116:119], v222 offset:8704
	ds_read_b64_tr_b16 v[148:149], v193 offset:0
	ds_read_b64_tr_b16 v[150:151], v193 offset:1088
	ds_read_b64_tr_b16 v[144:145], v193 offset:32
	ds_read_b64_tr_b16 v[146:147], v193 offset:1120
	ds_read_b64_tr_b16 v[140:141], v193 offset:64
	ds_read_b64_tr_b16 v[142:143], v193 offset:1152
	ds_read_b64_tr_b16 v[136:137], v193 offset:96
	ds_read_b64_tr_b16 v[138:139], v193 offset:1184
	ds_read_b64_tr_b16 v[132:133], v193 offset:128
	ds_read_b64_tr_b16 v[134:135], v193 offset:1216
	ds_read_b64_tr_b16 v[128:129], v193 offset:160
	ds_read_b64_tr_b16 v[130:131], v193 offset:1248
	ds_read_b64_tr_b16 v[124:125], v193 offset:192
	ds_read_b64_tr_b16 v[126:127], v193 offset:1280
	ds_read_b64_tr_b16 v[120:121], v193 offset:224
	ds_read_b64_tr_b16 v[122:123], v193 offset:1312
	s_waitcnt lgkmcnt(0)
	v_cmp_neq_f32_e32 vcc, 1.0, v184
	s_or_b64 vcc, s[6:7], vcc
	s_cbranch_vccz .LBB0_2554
	v_mov_b32_e32 v230, v185
	v_mov_b32_e32 v231, v184
	v_mov_b32_e32 v232, v161
	v_mov_b32_e32 v233, v160
	v_pk_mul_f32 v[62:63], v[62:63], v[230:231]
	v_pk_mul_f32 v[60:61], v[60:61], v[232:233]
	v_pk_mul_f32 v[58:59], v[58:59], v[230:231]
	v_pk_mul_f32 v[56:57], v[56:57], v[232:233]
	v_pk_mul_f32 v[54:55], v[54:55], v[230:231]
	v_pk_mul_f32 v[52:53], v[52:53], v[232:233]
	v_pk_mul_f32 v[50:51], v[50:51], v[230:231]
	v_pk_mul_f32 v[48:49], v[48:49], v[232:233]
	v_pk_mul_f32 v[46:47], v[46:47], v[230:231]
	v_pk_mul_f32 v[44:45], v[44:45], v[232:233]
	v_pk_mul_f32 v[42:43], v[42:43], v[230:231]
	v_pk_mul_f32 v[40:41], v[40:41], v[232:233]
	v_pk_mul_f32 v[38:39], v[38:39], v[230:231]
	v_pk_mul_f32 v[36:37], v[36:37], v[232:233]
	v_pk_mul_f32 v[34:35], v[34:35], v[230:231]
	v_pk_mul_f32 v[32:33], v[32:33], v[232:233]

.LBB0_2581:
	s_or_b64 exec, exec, s[12:13]
	v_lshl_add_u32 v2, v2, 2, v191
	ds_read_b128 v[128:131], v2
	v_add_f32_e32 v2, v118, v122
	v_add_f32_e32 v3, v116, v120
	v_add_f32_e32 v116, v117, v121
	v_cndmask_b32_e32 v117, v220, v2, vcc
	v_add_f32_e32 v2, v119, v123
	v_cndmask_b32_e32 v118, v220, v2, vcc
	s_waitcnt lgkmcnt(0)
	v_add_f32_e32 v2, v124, v128
	v_cndmask_b32_e32 v3, v220, v3, vcc
	v_cndmask_b32_e64 v2, v220, v2, s[6:7]
	v_max_f32_e32 v122, v3, v2
	v_add_f32_e32 v119, v125, v129
	v_cndmask_b32_e32 v116, v220, v116, vcc
	v_max_f32_dpp v122, v122, v122 quad_perm:[1,0,3,2] row_mask:0xf bank_mask:0xf bound_ctrl:1
	v_cndmask_b32_e64 v119, v220, v119, s[6:7]
	v_add_f32_e32 v120, v126, v130
	v_max_f32_dpp v122, v122, v122 quad_perm:[2,3,0,1] row_mask:0xf bank_mask:0xf bound_ctrl:1
	v_cndmask_b32_e64 v120, v220, v120, s[6:7]
	v_add_f32_e32 v121, v127, v131
	v_max_f32_dpp v122, v122, v122 row_half_mirror row_mask:0xf bank_mask:0xf bound_ctrl:1
	v_cndmask_b32_e64 v121, v220, v121, s[6:7]
	s_nop 0
	v_mov_b32_dpp v123, v122 row_mirror row_mask:0xf bank_mask:0xf bound_ctrl:1
	v_max3_f32 v233, v0, v122, v123
	v_sub_f32_e32 v3, v3, v233
	v_mul_f32_e32 v3, 0x3fb8aa3b, v3
	v_sub_f32_e32 v2, v2, v233
	v_exp_f32_e32 v3, v3
	v_mul_f32_e32 v2, 0x3fb8aa3b, v2
	v_exp_f32_e32 v159, v2
	v_sub_f32_e32 v0, v0, v233
	v_mul_f32_e32 v0, 0x3fb8aa3b, v0
	v_exp_f32_e32 v161, v0
	v_cvt_pk_bf16_f32 v0, v3, s0
	ds_write_b16 v221, v0 offset:8704
	v_cvt_pk_bf16_f32 v0, v159, s0
	ds_write_b16 v221, v0 offset:8736
	v_max_f32_e32 v0, v116, v119
	v_cmp_neq_f32_e32 vcc, 1.0, v161
	s_nop 0
	v_max_f32_dpp v0, v0, v0 quad_perm:[1,0,3,2] row_mask:0xf bank_mask:0xf bound_ctrl:1
	s_nop 1
	v_max_f32_dpp v0, v0, v0 quad_perm:[2,3,0,1] row_mask:0xf bank_mask:0xf bound_ctrl:1
	s_nop 1
	v_max_f32_dpp v0, v0, v0 row_half_mirror row_mask:0xf bank_mask:0xf bound_ctrl:1
	s_nop 1
	v_mov_b32_dpp v2, v0 row_mirror row_mask:0xf bank_mask:0xf bound_ctrl:1
	v_max3_f32 v232, v226, v0, v2
	v_sub_f32_e32 v2, v116, v232
	v_mul_f32_e32 v2, 0x3fb8aa3b, v2
	v_sub_f32_e32 v116, v119, v232
	v_exp_f32_e32 v2, v2
	v_mul_f32_e32 v116, 0x3fb8aa3b, v116
	v_exp_f32_e32 v158, v116
	v_sub_f32_e32 v0, v226, v232
	v_mul_f32_e32 v0, 0x3fb8aa3b, v0
	v_exp_f32_e32 v160, v0
	v_cvt_pk_bf16_f32 v0, v2, s0
	ds_write_b16 v221, v0 offset:8784
	v_cvt_pk_bf16_f32 v0, v158, s0
	ds_write_b16 v221, v0 offset:8816
	v_max_f32_e32 v0, v117, v120
	v_cmp_neq_f32_e64 s[6:7], 1.0, v160
	s_or_b64 s[6:7], vcc, s[6:7]
	v_max_f32_dpp v0, v0, v0 quad_perm:[1,0,3,2] row_mask:0xf bank_mask:0xf bound_ctrl:1
	s_nop 1
	v_max_f32_dpp v0, v0, v0 quad_perm:[2,3,0,1] row_mask:0xf bank_mask:0xf bound_ctrl:1
	s_nop 1
	v_max_f32_dpp v0, v0, v0 row_half_mirror row_mask:0xf bank_mask:0xf bound_ctrl:1
	s_nop 1
	v_mov_b32_dpp v116, v0 row_mirror row_mask:0xf bank_mask:0xf bound_ctrl:1
	v_max3_f32 v231, v227, v0, v116
	v_sub_f32_e32 v116, v117, v231
	v_mul_f32_e32 v116, 0x3fb8aa3b, v116
	v_exp_f32_e32 v181, v116
	v_sub_f32_e32 v116, v120, v231
	v_mul_f32_e32 v116, 0x3fb8aa3b, v116
	v_exp_f32_e32 v183, v116
	v_sub_f32_e32 v0, v227, v231
	v_mul_f32_e32 v0, 0x3fb8aa3b, v0
	v_exp_f32_e32 v185, v0
	v_cvt_pk_bf16_f32 v0, v181, s0
	ds_write_b16 v221, v0 offset:8864
	v_cvt_pk_bf16_f32 v0, v183, s0
	ds_write_b16 v221, v0 offset:8896
	v_max_f32_e32 v0, v118, v121
	v_cmp_neq_f32_e32 vcc, 1.0, v185
	s_or_b64 s[6:7], s[6:7], vcc
	v_max_f32_dpp v0, v0, v0 quad_perm:[1,0,3,2] row_mask:0xf bank_mask:0xf bound_ctrl:1
	s_nop 1
	v_max_f32_dpp v0, v0, v0 quad_perm:[2,3,0,1] row_mask:0xf bank_mask:0xf bound_ctrl:1
	s_nop 1
	v_max_f32_dpp v0, v0, v0 row_half_mirror row_mask:0xf bank_mask:0xf bound_ctrl:1
	s_nop 1
	v_mov_b32_dpp v116, v0 row_mirror row_mask:0xf bank_mask:0xf bound_ctrl:1
	v_max3_f32 v230, v224, v0, v116
	v_sub_f32_e32 v116, v118, v230
	v_mul_f32_e32 v116, 0x3fb8aa3b, v116
	v_exp_f32_e32 v180, v116
	v_sub_f32_e32 v116, v121, v230
	v_mul_f32_e32 v116, 0x3fb8aa3b, v116
	v_exp_f32_e32 v182, v116
	v_sub_f32_e32 v0, v224, v230
	v_mul_f32_e32 v0, 0x3fb8aa3b, v0
	v_exp_f32_e32 v184, v0
	v_cvt_pk_bf16_f32 v0, v180, s0
	ds_write_b16 v221, v0 offset:8944
	v_cvt_pk_bf16_f32 v0, v182, s0
	ds_write_b16 v221, v0 offset:8976
	s_waitcnt lgkmcnt(0)
	ds_read_b128 v[116:119], v222 offset:8704
	ds_read_b64_tr_b16 v[148:149], v193 offset:0
	ds_read_b64_tr_b16 v[150:151], v193 offset:1088
	ds_read_b64_tr_b16 v[144:145], v193 offset:32
	ds_read_b64_tr_b16 v[146:147], v193 offset:1120
	ds_read_b64_tr_b16 v[140:141], v193 offset:64
	ds_read_b64_tr_b16 v[142:143], v193 offset:1152
	ds_read_b64_tr_b16 v[136:137], v193 offset:96
	ds_read_b64_tr_b16 v[138:139], v193 offset:1184
	ds_read_b64_tr_b16 v[132:133], v193 offset:128
	ds_read_b64_tr_b16 v[134:135], v193 offset:1216
	ds_read_b64_tr_b16 v[128:129], v193 offset:160
	ds_read_b64_tr_b16 v[130:131], v193 offset:1248
	ds_read_b64_tr_b16 v[124:125], v193 offset:192
	ds_read_b64_tr_b16 v[126:127], v193 offset:1280
	ds_read_b64_tr_b16 v[120:121], v193 offset:224
	ds_read_b64_tr_b16 v[122:123], v193 offset:1312
	s_waitcnt lgkmcnt(0)
	v_cmp_neq_f32_e32 vcc, 1.0, v184
	s_or_b64 vcc, s[6:7], vcc
	s_cbranch_vccz .LBB0_2583
	v_mov_b32_e32 v226, v185
	v_mov_b32_e32 v227, v184
	v_mov_b32_e32 v228, v161
	v_mov_b32_e32 v229, v160
	v_pk_mul_f32 v[62:63], v[62:63], v[226:227]
	v_pk_mul_f32 v[60:61], v[60:61], v[228:229]
	v_pk_mul_f32 v[58:59], v[58:59], v[226:227]
	v_pk_mul_f32 v[56:57], v[56:57], v[228:229]
	v_pk_mul_f32 v[54:55], v[54:55], v[226:227]
	v_pk_mul_f32 v[52:53], v[52:53], v[228:229]
	v_pk_mul_f32 v[50:51], v[50:51], v[226:227]
	v_pk_mul_f32 v[48:49], v[48:49], v[228:229]
	v_pk_mul_f32 v[46:47], v[46:47], v[226:227]
	v_pk_mul_f32 v[44:45], v[44:45], v[228:229]
	v_pk_mul_f32 v[42:43], v[42:43], v[226:227]
	v_pk_mul_f32 v[40:41], v[40:41], v[228:229]
	v_pk_mul_f32 v[38:39], v[38:39], v[226:227]
	v_pk_mul_f32 v[36:37], v[36:37], v[228:229]
	v_pk_mul_f32 v[34:35], v[34:35], v[226:227]
	v_pk_mul_f32 v[32:33], v[32:33], v[228:229]

.LBB0_2600:
	v_cmp_eq_u32_e32 vcc, v2, v0
	s_and_b64 s[6:7], vcc, s[6:7]
	v_cndmask_b32_e64 v3, 0, 1, s[6:7]
	v_cmp_ne_u32_e32 vcc, 0, v3
	s_nop 1
	v_mbcnt_lo_u32_b32 v17, vcc_lo, 0
	v_mbcnt_hi_u32_b32 v3, vcc_hi, v17
	v_add_u32_e32 v3, s41, v3
	v_cmp_gt_u32_e64 s[8:9], s58, v3
	s_nop 1
	v_cndmask_b32_e64 v3, 0, 1, s[8:9]
	v_cmp_gt_u32_e64 s[8:9], v2, v0
	s_nop 1
	v_cndmask_b32_e64 v2, 0, 1, s[8:9]
	v_cndmask_b32_e64 v2, v2, v3, s[6:7]
	v_and_b32_e32 v2, 1, v2
	v_cmp_eq_u32_e64 s[8:9], 1, v2
	v_cmp_ne_u32_e64 s[6:7], 0, v2
	s_and_saveexec_b64 s[10:11], s[8:9]
	s_cbranch_execz .LBB0_2602
	ds_read_b32 v3, v190 offset:4608
	v_and_b32_e32 v17, s6, v168
	s_lshl_b32 s8, s40, 2
	v_and_b32_e32 v2, s7, v169
	v_bcnt_u32_b32 v17, v17, 0
	s_add_i32 s8, s43, s8
	v_bcnt_u32_b32 v2, v2, v17
	v_lshl_add_u32 v2, v2, 2, s8
	s_waitcnt lgkmcnt(0)
	ds_write_b32 v2, v3

.LBB0_2604:
	v_cmp_eq_u32_e32 vcc, v15, v0
	v_cmp_gt_u32_e64 s[6:7], s56, v197
	s_and_b64 s[6:7], vcc, s[6:7]
	s_nop 0
	v_cndmask_b32_e64 v2, 0, 1, s[6:7]
	v_cmp_ne_u32_e32 vcc, 0, v2
	s_nop 1
	v_mbcnt_lo_u32_b32 v3, vcc_lo, 0
	v_mbcnt_hi_u32_b32 v2, vcc_hi, v3
	v_add_u32_e32 v2, s41, v2
	v_cmp_gt_u32_e64 s[8:9], s58, v2
	s_nop 1
	v_cndmask_b32_e64 v2, 0, 1, s[8:9]
	v_cmp_gt_u32_e64 s[8:9], v15, v0
	s_nop 1
	v_cndmask_b32_e64 v3, 0, 1, s[8:9]
	v_cndmask_b32_e64 v2, v3, v2, s[6:7]
	v_and_b32_e32 v2, 1, v2
	v_cmp_ne_u32_e64 s[6:7], 0, v2
	v_cmp_eq_u32_e64 s[8:9], 1, v2
	s_nop 0
	v_mbcnt_lo_u32_b32 v3, s6, 0
	v_mbcnt_hi_u32_b32 v2, s7, v3
	v_add_u32_e32 v2, s40, v2
	v_cmp_gt_u32_e64 s[10:11], s48, v2
	s_and_b64 s[10:11], s[8:9], s[10:11]
	s_and_saveexec_b64 s[8:9], s[10:11]
	s_cbranch_execz .LBB0_2606
	ds_read_b32 v3, v190 offset:5120
	v_lshl_add_u32 v2, v2, 2, s43
	s_waitcnt lgkmcnt(0)
	ds_write_b32 v2, v3

.LBB0_2608:
	v_cmp_eq_u32_e32 vcc, v13, v0
	v_cmp_gt_u32_e64 s[6:7], s56, v199
	s_and_b64 s[6:7], vcc, s[6:7]
	s_nop 0
	v_cndmask_b32_e64 v2, 0, 1, s[6:7]
	v_cmp_ne_u32_e32 vcc, 0, v2
	s_nop 1
	v_mbcnt_lo_u32_b32 v3, vcc_lo, 0
	v_mbcnt_hi_u32_b32 v2, vcc_hi, v3
	v_add_u32_e32 v2, s41, v2
	v_cmp_gt_u32_e64 s[8:9], s58, v2
	s_nop 1
	v_cndmask_b32_e64 v2, 0, 1, s[8:9]
	v_cmp_gt_u32_e64 s[8:9], v13, v0
	s_nop 1
	v_cndmask_b32_e64 v3, 0, 1, s[8:9]
	v_cndmask_b32_e64 v2, v3, v2, s[6:7]
	v_and_b32_e32 v2, 1, v2
	v_cmp_ne_u32_e64 s[6:7], 0, v2
	v_cmp_eq_u32_e64 s[8:9], 1, v2
	s_nop 0
	v_mbcnt_lo_u32_b32 v3, s6, 0
	v_mbcnt_hi_u32_b32 v2, s7, v3
	v_add_u32_e32 v2, s40, v2
	v_cmp_gt_u32_e64 s[10:11], s48, v2
	s_and_b64 s[10:11], s[8:9], s[10:11]
	s_and_saveexec_b64 s[8:9], s[10:11]
	s_cbranch_execz .LBB0_2610
	ds_read_b32 v3, v190 offset:5632
	v_lshl_add_u32 v2, v2, 2, s43
	s_waitcnt lgkmcnt(0)
	ds_write_b32 v2, v3

.LBB0_2612:
	v_cmp_eq_u32_e32 vcc, v11, v0
	v_cmp_gt_u32_e64 s[6:7], s56, v201
	s_and_b64 s[6:7], vcc, s[6:7]
	s_nop 0
	v_cndmask_b32_e64 v2, 0, 1, s[6:7]
	v_cmp_ne_u32_e32 vcc, 0, v2
	s_nop 1
	v_mbcnt_lo_u32_b32 v3, vcc_lo, 0
	v_mbcnt_hi_u32_b32 v2, vcc_hi, v3
	v_add_u32_e32 v2, s41, v2
	v_cmp_gt_u32_e64 s[8:9], s58, v2
	s_nop 1
	v_cndmask_b32_e64 v2, 0, 1, s[8:9]
	v_cmp_gt_u32_e64 s[8:9], v11, v0
	s_nop 1
	v_cndmask_b32_e64 v3, 0, 1, s[8:9]
	v_cndmask_b32_e64 v2, v3, v2, s[6:7]
	v_and_b32_e32 v2, 1, v2
	v_cmp_ne_u32_e64 s[6:7], 0, v2
	v_cmp_eq_u32_e64 s[8:9], 1, v2
	s_nop 0
	v_mbcnt_lo_u32_b32 v3, s6, 0
	v_mbcnt_hi_u32_b32 v2, s7, v3
	v_add_u32_e32 v2, s40, v2
	v_cmp_gt_u32_e64 s[10:11], s48, v2
	s_and_b64 s[10:11], s[8:9], s[10:11]
	s_and_saveexec_b64 s[8:9], s[10:11]
	s_cbranch_execz .LBB0_2614
	ds_read_b32 v3, v190 offset:6144
	v_lshl_add_u32 v2, v2, 2, s43
	s_waitcnt lgkmcnt(0)
	ds_write_b32 v2, v3

.LBB0_2616:
	v_cmp_eq_u32_e32 vcc, v9, v0
	v_cmp_gt_u32_e64 s[6:7], s56, v203
	s_and_b64 s[6:7], vcc, s[6:7]
	s_nop 0
	v_cndmask_b32_e64 v2, 0, 1, s[6:7]
	v_cmp_ne_u32_e32 vcc, 0, v2
	s_nop 1
	v_mbcnt_lo_u32_b32 v3, vcc_lo, 0
	v_mbcnt_hi_u32_b32 v2, vcc_hi, v3
	v_add_u32_e32 v2, s41, v2
	v_cmp_gt_u32_e64 s[8:9], s58, v2
	s_nop 1
	v_cndmask_b32_e64 v2, 0, 1, s[8:9]
	v_cmp_gt_u32_e64 s[8:9], v9, v0
	s_nop 1
	v_cndmask_b32_e64 v3, 0, 1, s[8:9]
	v_cndmask_b32_e64 v2, v3, v2, s[6:7]
	v_and_b32_e32 v2, 1, v2
	v_cmp_ne_u32_e64 s[6:7], 0, v2
	v_cmp_eq_u32_e64 s[8:9], 1, v2
	s_nop 0
	v_mbcnt_lo_u32_b32 v3, s6, 0
	v_mbcnt_hi_u32_b32 v2, s7, v3
	v_add_u32_e32 v2, s40, v2
	v_cmp_gt_u32_e64 s[10:11], s48, v2
	s_and_b64 s[10:11], s[8:9], s[10:11]
	s_and_saveexec_b64 s[8:9], s[10:11]
	s_cbranch_execz .LBB0_2618
	ds_read_b32 v3, v190 offset:6656
	v_lshl_add_u32 v2, v2, 2, s43
	s_waitcnt lgkmcnt(0)
	ds_write_b32 v2, v3

.LBB0_2620:
	v_cmp_eq_u32_e32 vcc, v7, v0
	v_cmp_gt_u32_e64 s[6:7], s56, v205
	s_and_b64 s[6:7], vcc, s[6:7]
	s_nop 0
	v_cndmask_b32_e64 v2, 0, 1, s[6:7]
	v_cmp_ne_u32_e32 vcc, 0, v2
	s_nop 1
	v_mbcnt_lo_u32_b32 v3, vcc_lo, 0
	v_mbcnt_hi_u32_b32 v2, vcc_hi, v3
	v_add_u32_e32 v2, s41, v2
	v_cmp_gt_u32_e64 s[8:9], s58, v2
	s_nop 1
	v_cndmask_b32_e64 v2, 0, 1, s[8:9]
	v_cmp_gt_u32_e64 s[8:9], v7, v0
	s_nop 1
	v_cndmask_b32_e64 v3, 0, 1, s[8:9]
	v_cndmask_b32_e64 v2, v3, v2, s[6:7]
	v_and_b32_e32 v2, 1, v2
	v_cmp_ne_u32_e64 s[6:7], 0, v2
	v_cmp_eq_u32_e64 s[8:9], 1, v2
	s_nop 0
	v_mbcnt_lo_u32_b32 v3, s6, 0
	v_mbcnt_hi_u32_b32 v2, s7, v3
	v_add_u32_e32 v2, s40, v2
	v_cmp_gt_u32_e64 s[10:11], s48, v2
	s_and_b64 s[10:11], s[8:9], s[10:11]
	s_and_saveexec_b64 s[8:9], s[10:11]
	s_cbranch_execz .LBB0_2622
	ds_read_b32 v3, v190 offset:7168
	v_lshl_add_u32 v2, v2, 2, s43
	s_waitcnt lgkmcnt(0)
	ds_write_b32 v2, v3

.LBB0_2624:
	v_cmp_eq_u32_e32 vcc, v5, v0
	v_cmp_gt_u32_e64 s[6:7], s56, v207
	s_and_b64 s[6:7], vcc, s[6:7]
	s_nop 0
	v_cndmask_b32_e64 v2, 0, 1, s[6:7]
	v_cmp_ne_u32_e32 vcc, 0, v2
	s_nop 1
	v_mbcnt_lo_u32_b32 v3, vcc_lo, 0
	v_mbcnt_hi_u32_b32 v2, vcc_hi, v3
	v_add_u32_e32 v2, s41, v2
	v_cmp_gt_u32_e64 s[8:9], s58, v2
	s_nop 1
	v_cndmask_b32_e64 v2, 0, 1, s[8:9]
	v_cmp_gt_u32_e64 s[8:9], v5, v0
	s_nop 1
	v_cndmask_b32_e64 v3, 0, 1, s[8:9]
	v_cndmask_b32_e64 v2, v3, v2, s[6:7]
	v_and_b32_e32 v2, 1, v2
	v_cmp_ne_u32_e64 s[6:7], 0, v2
	v_cmp_eq_u32_e64 s[8:9], 1, v2
	s_nop 0
	v_mbcnt_lo_u32_b32 v3, s6, 0
	v_mbcnt_hi_u32_b32 v2, s7, v3
	v_add_u32_e32 v2, s40, v2
	v_cmp_gt_u32_e64 s[10:11], s48, v2
	s_and_b64 s[10:11], s[8:9], s[10:11]
	s_and_saveexec_b64 s[8:9], s[10:11]
	s_cbranch_execz .LBB0_2626
	ds_read_b32 v3, v190 offset:7680
	v_lshl_add_u32 v2, v2, 2, s43
	s_waitcnt lgkmcnt(0)
	ds_write_b32 v2, v3

.LBB0_2627:
	v_cmp_eq_u32_e32 vcc, v4, v0
	v_cmp_gt_u32_e64 s[6:7], s56, v208
	s_and_b64 vcc, vcc, s[6:7]
	v_cndmask_b32_e64 v2, 0, 1, vcc
	v_cmp_ne_u32_e64 s[6:7], 0, v2
	s_nop 1
	v_mbcnt_lo_u32_b32 v3, s6, 0
	v_mbcnt_hi_u32_b32 v2, s7, v3
	v_add_u32_e32 v2, s41, v2
	v_cmp_gt_u32_e64 s[6:7], s58, v2
	s_nop 1
	v_cndmask_b32_e64 v2, 0, 1, s[6:7]
	v_cmp_gt_u32_e64 s[6:7], v4, v0
	s_nop 1
	v_cndmask_b32_e64 v0, 0, 1, s[6:7]
	v_cndmask_b32_e32 v0, v0, v2, vcc
	v_and_b32_e32 v0, 1, v0
	v_cmp_ne_u32_e64 s[6:7], 0, v0
	v_cmp_eq_u32_e32 vcc, 1, v0
	s_nop 0
	v_mbcnt_lo_u32_b32 v2, s6, 0
	v_mbcnt_hi_u32_b32 v0, s7, v2
	v_add_u32_e32 v0, s40, v0
	v_cmp_gt_u32_e64 s[6:7], s48, v0
	s_and_b64 s[8:9], vcc, s[6:7]
	s_and_saveexec_b64 s[6:7], s[8:9]
	s_cbranch_execz .LBB0_2629
	ds_read_b32 v2, v190 offset:7936
	v_lshl_add_u32 v0, v0, 2, s43
	s_waitcnt lgkmcnt(0)
	ds_write_b32 v0, v2
